# ssm_local_unit2: next unit's pr=0 U fragments prefetched into dedicated VGPRs during pr=1; loop top issues Bcat/abar loads first, uf[2..3] last with relaxed counted waits
# baseline (speedup 1.0000x reference)
.LBB0_324:
	s_cmpk_gt_i32 s2, 0x1ff
	s_cbranch_scc1 .LBB0_327
	s_mul_i32 s0, s3, 0x4400
	v_mul_u32_u24_e32 v2, 0x88, v124
	s_add_i32 s0, s0, 0
	v_lshlrev_b32_e32 v88, 1, v141
	v_mov_b32_e32 v89, 0
	v_lshlrev_b32_e32 v2, 1, v2
	v_lshlrev_b32_e32 v3, 1, v129
	s_lshl_b32 s8, s3, 4
	v_lshl_add_u64 v[0:1], s[62:63], 0, v[88:89]
	s_mov_b64 s[6:7], 0x1c30000
	v_add3_u32 v125, s0, v2, v3
	v_lshlrev_b32_e32 v2, 3, v193
	v_mov_b32_e32 v3, v89
	s_add_u32 s4, s62, 0x1c20000
	v_lshl_add_u64 v[0:1], v[0:1], 0, s[6:7]
	v_lshl_add_u64 v[2:3], s[62:63], 0, v[2:3]
	s_mov_b64 s[6:7], 0x2200000
	s_addc_u32 s5, s63, 0
	v_lshl_add_u64 v[90:91], v[2:3], 0, s[6:7]
	s_waitcnt lgkmcnt(0)
	s_add_i32 s12, s3, 8
	v_lshl_or_b32 v2, s3, 7, v124
	v_mov_b32_e32 v3, v89
	v_lshl_or_b32 v4, s12, 7, v124
	v_lshlrev_b64 v[6:7], 5, v[2:3]
	v_mov_b32_e32 v5, v89
	v_lshl_add_u64 v[92:93], v[0:1], 0, v[6:7]
	v_lshlrev_b64 v[6:7], 5, v[4:5]
	v_lshl_add_u64 v[94:95], v[0:1], 0, v[6:7]
	v_or_b32_e32 v6, 32, v2
	v_mov_b32_e32 v7, v89
	v_lshlrev_b64 v[6:7], 5, v[6:7]
	v_lshl_add_u64 v[96:97], v[0:1], 0, v[6:7]
	v_or_b32_e32 v6, 32, v4
	v_mov_b32_e32 v7, v89
	v_lshlrev_b64 v[6:7], 5, v[6:7]
	v_lshl_add_u64 v[98:99], v[0:1], 0, v[6:7]
	v_or_b32_e32 v6, 64, v2
	v_or_b32_e32 v2, 0x60, v2
	v_lshlrev_b64 v[2:3], 5, v[2:3]
	v_lshl_add_u64 v[104:105], v[0:1], 0, v[2:3]
	v_or_b32_e32 v2, 0x60, v4
	v_mov_b32_e32 v3, v89
	v_lshl_add_u32 v145, v193, 2, s0
	v_lshlrev_b64 v[2:3], 5, v[2:3]
	s_and_b32 s0, s91, 0xffffffc0
	v_mov_b32_e32 v7, v89
	v_lshl_add_u64 v[106:107], v[0:1], 0, v[2:3]
	v_or_b32_e32 v2, s0, v193
	v_lshlrev_b64 v[6:7], 5, v[6:7]
	v_ashrrev_i32_e32 v3, 31, v2
	v_lshl_add_u64 v[100:101], v[0:1], 0, v[6:7]
	v_or_b32_e32 v6, 64, v4
	v_mov_b32_e32 v7, v89
	v_lshl_add_u64 v[108:109], v[2:3], 3, s[4:5]
	v_lshl_or_b32 v2, s12, 6, v193
	v_mov_b32_e32 v3, v89
	s_add_i32 s13, s3, 16
	v_lshlrev_b64 v[6:7], 5, v[6:7]
	v_lshl_add_u64 v[110:111], v[2:3], 3, s[4:5]
	s_add_i32 s14, s3, 24
	v_lshl_or_b32 v2, s13, 7, v124
	v_lshl_add_u64 v[102:103], v[0:1], 0, v[6:7]
	v_lshl_or_b32 v4, s14, 7, v124
	v_lshlrev_b64 v[6:7], 5, v[2:3]
	v_lshl_add_u64 v[112:113], v[0:1], 0, v[6:7]
	v_lshlrev_b64 v[6:7], 5, v[4:5]
	v_lshl_add_u64 v[114:115], v[0:1], 0, v[6:7]
	v_or_b32_e32 v6, 32, v2
	v_mov_b32_e32 v7, v89
	v_lshlrev_b64 v[6:7], 5, v[6:7]
	v_lshl_add_u64 v[116:117], v[0:1], 0, v[6:7]
	v_or_b32_e32 v6, 32, v4
	v_mov_b32_e32 v7, v89
	v_lshlrev_b64 v[6:7], 5, v[6:7]
	v_lshl_add_u64 v[118:119], v[0:1], 0, v[6:7]
	v_or_b32_e32 v6, 64, v2
	v_mov_b32_e32 v7, v89
	v_or_b32_e32 v2, 0x60, v2
	v_lshlrev_b64 v[6:7], 5, v[6:7]
	v_lshlrev_b64 v[2:3], 5, v[2:3]
	v_lshl_add_u64 v[120:121], v[0:1], 0, v[6:7]
	v_or_b32_e32 v6, 64, v4
	v_mov_b32_e32 v7, v89
	v_lshl_add_u64 v[126:127], v[0:1], 0, v[2:3]
	v_or_b32_e32 v2, 0x60, v4
	v_mov_b32_e32 v3, v89
	v_lshlrev_b64 v[6:7], 5, v[6:7]
	v_lshlrev_b64 v[2:3], 5, v[2:3]
	v_lshl_add_u64 v[122:123], v[0:1], 0, v[6:7]
	v_lshl_add_u64 v[128:129], v[0:1], 0, v[2:3]
	v_lshl_or_b32 v0, s13, 6, v193
	v_mov_b32_e32 v1, v89
	v_lshl_add_u64 v[130:131], v[0:1], 3, s[4:5]
	v_lshl_or_b32 v0, s14, 6, v193
	s_mov_b32 s1, 0
	v_lshl_add_u64 v[132:133], v[0:1], 3, s[4:5]
	s_lshl_b32 s15, s2, 6
	s_lshl_b32 s16, s82, 6
	s_movk_i32 s17, 0x2400
	s_lshl_b32 s0, s8, 1
	s_mov_b64 s[4:5], 0xc001c00
	s_mov_b32 s18, 0xc001000
	s_mov_b64 s[6:7], 0xc049c00
	s_mov_b32 s19, 0xc049000
	v_mov_b64_e32 v[134:135], s[62:63]
	v_mov_b32_e32 v147, 0x2400
	v_add_u32_e32 v192, 0x2000, v125
	s_mov_b32 s8, s2
	s_mul_i32 s100, s8, 64
	v_or_b32_e32 v250, s100, v124
	v_mul_u32_u24_e32 v250, 0x2400, v250
	v_mov_b32_e32 v251, 0
	v_lshl_add_u64 v[250:251], v[250:251], 0, v[134:135]
	v_lshl_add_u64 v[250:251], v[250:251], 0, s[0:1]
	v_lshl_add_u64 v[250:251], v[250:251], 0, v[88:89]
	v_lshl_add_u64 v[252:253], v[250:251], 0, s[4:5]
	v_lshl_add_u64 v[254:255], v[250:251], 0, s[6:7]
	global_load_dwordx4 v[218:221], v[252:253], off
	global_load_dwordx4 v[226:229], v[252:253], off offset:256
	global_load_dwordx4 v[222:225], v[254:255], off
	global_load_dwordx4 v[230:233], v[254:255], off offset:256
.LBB0_326:
	s_ashr_i32 s9, s8, 31
	s_lshr_b32 s10, s9, 24
	s_add_i32 s10, s8, s10
	s_ashr_i32 s10, s10, 8
	s_ashr_i32 s11, s10, 31
	s_lshl_b64 s[20:21], s[10:11], 14
	s_lshl_b32 s10, s10, 14
	s_sub_i32 s10, s15, s10
	s_ashr_i32 s11, s10, 31
	s_add_u32 s10, s20, s10
	v_or_b32_e32 v0, s10, v124
	s_addc_u32 s20, s21, s11
	v_mad_u64_u32 v[0:1], s[10:11], v0, s17, v[134:135]
	v_mad_i32_i24 v1, s20, v147, v1
	v_lshl_add_u64 v[0:1], v[0:1], 0, s[0:1]
	v_lshl_add_u64 v[0:1], v[0:1], 0, v[88:89]
	v_add_co_u32_e32 v4, vcc, s18, v0
	v_lshl_add_u64 v[2:3], v[0:1], 0, s[4:5]
	s_nop 0
	v_addc_co_u32_e32 v5, vcc, 0, v1, vcc
	v_lshl_add_u64 v[4:5], v[0:1], 0, s[6:7]
	v_add_co_u32_e32 v0, vcc, s19, v0
	v_add_u32_e32 v215, 0x2000, v145
	s_nop 0
	v_addc_co_u32_e32 v1, vcc, 0, v1, vcc
	global_load_dwordx4 v[84:87], v[92:93], off
	global_load_dwordx4 v[80:83], v[94:95], off
	global_load_dwordx4 v[76:79], v[96:97], off
	global_load_dwordx4 v[72:75], v[98:99], off
	global_load_dwordx4 v[68:71], v[100:101], off
	global_load_dwordx4 v[64:67], v[102:103], off
	global_load_dwordx4 v[60:63], v[104:105], off
	global_load_dwordx4 v[56:59], v[106:107], off
	global_load_dwordx2 v[140:141], v[108:109], off
	global_load_dwordx2 v[136:137], v[110:111], off
	global_load_dwordx4 v[44:47], v[2:3], off offset:512
	global_load_dwordx4 v[36:39], v[4:5], off offset:512
	global_load_dwordx4 v[40:43], v[2:3], off offset:768
	global_load_dwordx4 v[32:35], v[4:5], off offset:768
	v_add_u32_e32 v216, 0x2400, v145
	v_add_u32_e32 v217, 0x400, v145
	v_add_u32_e32 v210, 0x2800, v145
	v_add_u32_e32 v211, 0x800, v145
	v_add_u32_e32 v212, 0x2c00, v145
	v_add_u32_e32 v213, 0xc00, v145
	v_add_u32_e32 v202, 0x1000, v145
	v_add_u32_e32 v203, 0x3200, v145
	v_add_u32_e32 v204, 0x1200, v145
	v_add_u32_e32 v214, 0x3000, v145
	v_add_u32_e32 v205, 0x3400, v145
	v_add_u32_e32 v206, 0x1400, v145
	v_add_u32_e32 v207, 0x3600, v145
	v_add_u32_e32 v208, 0x1600, v145
	v_add_u32_e32 v209, 0x3800, v145
	v_add_u32_e32 v194, 0x1800, v145
	v_add_u32_e32 v195, 0x3a00, v145
	v_add_u32_e32 v196, 0x1a00, v145
	v_add_u32_e32 v197, 0x3c00, v145
	v_add_u32_e32 v198, 0x1c00, v145
	v_add_u32_e32 v199, 0x3e00, v145
	v_add_u32_e32 v200, 0x1e00, v145
	v_add_u32_e32 v201, 0x4000, v145
	s_lshl_b64 s[10:11], s[8:9], 5
	s_add_u32 s20, s10, s3
	s_addc_u32 s21, s11, 0
	s_lshl_b64 s[20:21], s[20:21], 9
	s_waitcnt vmcnt(12)
	v_mfma_f32_32x32x16_bf16 v[0:15], v[80:83], v[226:229], 0
	s_waitcnt vmcnt(5)
	v_xor_b32_e32 v143, 0x80000000, v141
	v_mov_b32_e32 v142, v141
	s_waitcnt vmcnt(4)
	v_xor_b32_e32 v139, 0x80000000, v137
	v_mfma_f32_32x32x16_bf16 v[16:31], v[84:87], v[218:221], 0
	s_nop 5
	v_cvt_pk_bf16_f32 v0, v0, v1
	v_cvt_pk_bf16_f32 v1, v2, v3
	v_mov_b32_e32 v138, v137
	s_nop 2
	v_cvt_pk_bf16_f32 v16, v16, v17
	v_cvt_pk_bf16_f32 v17, v18, v19
	v_cvt_pk_bf16_f32 v2, v20, v21
	v_cvt_pk_bf16_f32 v3, v22, v23
	ds_write2_b64 v125, v[16:17], v[2:3] offset1:2
	v_cvt_pk_bf16_f32 v2, v4, v5
	v_cvt_pk_bf16_f32 v3, v6, v7
	ds_write2_b64 v192, v[0:1], v[2:3] offset0:64 offset1:66
	v_cvt_pk_bf16_f32 v0, v24, v25
	v_cvt_pk_bf16_f32 v1, v26, v27
	v_cvt_pk_bf16_f32 v4, v28, v29
	v_cvt_pk_bf16_f32 v5, v30, v31
	v_cvt_pk_bf16_f32 v2, v8, v9
	v_cvt_pk_bf16_f32 v3, v10, v11
	ds_write2_b64 v125, v[0:1], v[4:5] offset0:4 offset1:6
	v_cvt_pk_bf16_f32 v0, v12, v13
	v_cvt_pk_bf16_f32 v1, v14, v15
	ds_write2_b64 v192, v[2:3], v[0:1] offset0:68 offset1:70
	v_mfma_f32_32x32x16_bf16 v[16:31], v[76:79], v[218:221], 0
	v_mfma_f32_32x32x16_bf16 v[0:15], v[72:75], v[226:229], 0
	s_nop 10
	v_cvt_pk_bf16_f32 v16, v16, v17
	v_cvt_pk_bf16_f32 v17, v18, v19
	v_cvt_pk_bf16_f32 v0, v0, v1
	v_cvt_pk_bf16_f32 v1, v2, v3
	v_cvt_pk_bf16_f32 v2, v20, v21
	v_cvt_pk_bf16_f32 v3, v22, v23
	ds_write2_b64 v125, v[16:17], v[2:3] offset0:8 offset1:10
	v_cvt_pk_bf16_f32 v2, v4, v5
	v_cvt_pk_bf16_f32 v3, v6, v7
	ds_write2_b64 v192, v[0:1], v[2:3] offset0:72 offset1:74
	v_cvt_pk_bf16_f32 v0, v24, v25
	v_cvt_pk_bf16_f32 v1, v26, v27
	v_cvt_pk_bf16_f32 v4, v28, v29
	v_cvt_pk_bf16_f32 v5, v30, v31
	v_cvt_pk_bf16_f32 v2, v8, v9
	v_cvt_pk_bf16_f32 v3, v10, v11
	ds_write2_b64 v125, v[0:1], v[4:5] offset0:12 offset1:14
	v_cvt_pk_bf16_f32 v0, v12, v13
	v_cvt_pk_bf16_f32 v1, v14, v15
	ds_write2_b64 v192, v[2:3], v[0:1] offset0:76 offset1:78
	v_mfma_f32_32x32x16_bf16 v[16:31], v[68:71], v[218:221], 0
	v_mfma_f32_32x32x16_bf16 v[0:15], v[64:67], v[226:229], 0
	s_nop 10
	v_cvt_pk_bf16_f32 v16, v16, v17
	v_cvt_pk_bf16_f32 v17, v18, v19
	v_cvt_pk_bf16_f32 v0, v0, v1
	v_cvt_pk_bf16_f32 v1, v2, v3
	v_cvt_pk_bf16_f32 v2, v20, v21
	v_cvt_pk_bf16_f32 v3, v22, v23
	ds_write2_b64 v125, v[16:17], v[2:3] offset0:16 offset1:18
	v_cvt_pk_bf16_f32 v2, v4, v5
	v_cvt_pk_bf16_f32 v3, v6, v7
	ds_write2_b64 v192, v[0:1], v[2:3] offset0:80 offset1:82
	v_cvt_pk_bf16_f32 v0, v24, v25
	v_cvt_pk_bf16_f32 v1, v26, v27
	v_cvt_pk_bf16_f32 v4, v28, v29
	v_cvt_pk_bf16_f32 v5, v30, v31
	v_cvt_pk_bf16_f32 v2, v8, v9
	v_cvt_pk_bf16_f32 v3, v10, v11
	ds_write2_b64 v125, v[0:1], v[4:5] offset0:20 offset1:22
	v_cvt_pk_bf16_f32 v0, v12, v13
	v_cvt_pk_bf16_f32 v1, v14, v15
	ds_write2_b64 v192, v[2:3], v[0:1] offset0:84 offset1:86
	v_mfma_f32_32x32x16_bf16 v[16:31], v[60:63], v[218:221], 0
	v_mov_b32_e32 v150, v143
	v_mov_b32_e32 v151, v141
	v_mov_b32_e32 v148, v139
	v_mov_b32_e32 v149, v137
	v_mfma_f32_32x32x16_bf16 v[0:15], v[56:59], v[226:229], 0
	s_nop 6
	v_cvt_pk_bf16_f32 v16, v16, v17
	v_cvt_pk_bf16_f32 v17, v18, v19
	s_nop 2
	v_cvt_pk_bf16_f32 v0, v0, v1
	v_cvt_pk_bf16_f32 v1, v2, v3
	v_cvt_pk_bf16_f32 v2, v20, v21
	v_cvt_pk_bf16_f32 v3, v22, v23
	ds_write2_b64 v125, v[16:17], v[2:3] offset0:24 offset1:26
	v_cvt_pk_bf16_f32 v2, v4, v5
	v_cvt_pk_bf16_f32 v3, v6, v7
	ds_write2_b64 v192, v[0:1], v[2:3] offset0:88 offset1:90
	v_cvt_pk_bf16_f32 v0, v24, v25
	v_cvt_pk_bf16_f32 v1, v26, v27
	v_cvt_pk_bf16_f32 v4, v28, v29
	v_cvt_pk_bf16_f32 v5, v30, v31
	v_cvt_pk_bf16_f32 v2, v8, v9
	v_cvt_pk_bf16_f32 v3, v10, v11
	ds_write2_b64 v125, v[0:1], v[4:5] offset0:28 offset1:30
	v_cvt_pk_bf16_f32 v0, v12, v13
	v_cvt_pk_bf16_f32 v1, v14, v15
	ds_write2_b64 v192, v[2:3], v[0:1] offset0:92 offset1:94
	s_waitcnt lgkmcnt(0)
	ds_read2_b32 v[0:1], v145 offset1:68
	ds_read2_b32 v[2:3], v215 offset0:128 offset1:196
	ds_read2_b32 v[4:5], v145 offset0:136 offset1:204
	ds_read2_b32 v[6:7], v216 offset0:8 offset1:76
	ds_read2_b32 v[10:11], v217 offset0:16 offset1:84
	ds_read2_b32 v[12:13], v216 offset0:144 offset1:212
	ds_read2_b32 v[14:15], v217 offset0:152 offset1:220
	ds_read2_b32 v[16:17], v210 offset0:24 offset1:92
	s_waitcnt lgkmcnt(7)
	v_lshlrev_b32_e32 v9, 16, v0
	v_and_b32_e32 v8, 0xffff0000, v0
	v_pk_fma_f32 v[8:9], v[142:143], 0, v[8:9] op_sel_hi:[1,0,1]
	v_lshlrev_b32_e32 v21, 16, v1
	v_and_b32_e32 v20, 0xffff0000, v1
	v_pk_fma_f32 v[8:9], v[140:141], 0, v[8:9] op_sel_hi:[0,0,1]
	v_pk_fma_f32 v[20:21], v[142:143], v[8:9], v[20:21] op_sel:[0,1,0] op_sel_hi:[1,0,1]
	s_waitcnt lgkmcnt(5)
	v_lshlrev_b32_e32 v1, 16, v4
	v_and_b32_e32 v0, 0xffff0000, v4
	v_pk_fma_f32 v[8:9], v[140:141], v[8:9], v[20:21] op_sel_hi:[0,1,1]
	v_lshlrev_b32_e32 v19, 16, v2
	v_and_b32_e32 v18, 0xffff0000, v2
	v_pk_fma_f32 v[0:1], v[142:143], v[8:9], v[0:1] op_sel:[0,1,0] op_sel_hi:[1,0,1]
	v_lshlrev_b32_e32 v23, 16, v3
	v_pk_fma_f32 v[0:1], v[140:141], v[8:9], v[0:1] op_sel_hi:[0,1,1]
	v_pk_fma_f32 v[8:9], v[138:139], 0, v[18:19] op_sel_hi:[1,0,1]
	v_and_b32_e32 v22, 0xffff0000, v3
	v_lshlrev_b32_e32 v4, 16, v5
	v_and_b32_e32 v5, 0xffff0000, v5
	v_pk_fma_f32 v[8:9], v[136:137], 0, v[8:9] op_sel_hi:[0,0,1]
	v_pk_fma_f32 v[4:5], v[150:151], v[0:1], v[4:5]
	v_pk_fma_f32 v[18:19], v[138:139], v[8:9], v[22:23] op_sel:[0,1,0] op_sel_hi:[1,0,1]
	s_waitcnt lgkmcnt(4)
	v_lshlrev_b32_e32 v3, 16, v6
	v_and_b32_e32 v2, 0xffff0000, v6
	v_pk_fma_f32 v[8:9], v[136:137], v[8:9], v[18:19] op_sel_hi:[0,1,1]
	s_waitcnt lgkmcnt(3)
	v_lshlrev_b32_e32 v18, 16, v10
	v_and_b32_e32 v19, 0xffff0000, v10
	v_pk_fma_f32 v[0:1], v[140:141], v[0:1], v[4:5] op_sel:[0,0,1] op_sel_hi:[0,1,0]
	v_pk_fma_f32 v[2:3], v[138:139], v[8:9], v[2:3] op_sel:[0,1,0] op_sel_hi:[1,0,1]
	v_pk_fma_f32 v[4:5], v[150:151], v[0:1], v[18:19]
	v_lshlrev_b32_e32 v6, 16, v7
	v_and_b32_e32 v7, 0xffff0000, v7
	v_pk_fma_f32 v[2:3], v[136:137], v[8:9], v[2:3] op_sel_hi:[0,1,1]
	v_lshlrev_b32_e32 v21, 16, v11
	v_and_b32_e32 v20, 0xffff0000, v11
	v_pk_fma_f32 v[0:1], v[140:141], v[0:1], v[4:5] op_sel:[0,0,1] op_sel_hi:[0,1,0]
	v_pk_fma_f32 v[6:7], v[148:149], v[2:3], v[6:7]
	v_pk_fma_f32 v[4:5], v[142:143], v[0:1], v[20:21] op_sel:[0,1,0] op_sel_hi:[1,0,1]
	s_waitcnt lgkmcnt(2)
	v_lshlrev_b32_e32 v8, 16, v12
	v_and_b32_e32 v9, 0xffff0000, v12
	s_waitcnt lgkmcnt(1)
	v_lshlrev_b32_e32 v23, 16, v14
	v_and_b32_e32 v22, 0xffff0000, v14
	v_pk_fma_f32 v[0:1], v[140:141], v[0:1], v[4:5] op_sel_hi:[0,1,1]
	v_pk_fma_f32 v[2:3], v[136:137], v[2:3], v[6:7] op_sel:[0,0,1] op_sel_hi:[0,1,0]
	v_lshlrev_b32_e32 v11, 16, v13
	v_and_b32_e32 v10, 0xffff0000, v13
	s_waitcnt lgkmcnt(0)
	v_lshlrev_b32_e32 v13, 16, v16
	v_and_b32_e32 v12, 0xffff0000, v16
	v_lshlrev_b32_e32 v25, 16, v15
	v_and_b32_e32 v24, 0xffff0000, v15
	v_lshlrev_b32_e32 v15, 16, v17
	v_and_b32_e32 v14, 0xffff0000, v17
	ds_read2_b32 v[16:17], v211 offset0:32 offset1:100
	ds_read2_b32 v[26:27], v210 offset0:160 offset1:228
	ds_read2_b32 v[28:29], v211 offset0:168 offset1:236
	v_pk_fma_f32 v[4:5], v[142:143], v[0:1], v[22:23] op_sel:[0,1,0] op_sel_hi:[1,0,1]
	v_pk_fma_f32 v[6:7], v[148:149], v[2:3], v[8:9]
	v_pk_fma_f32 v[0:1], v[140:141], v[0:1], v[4:5] op_sel_hi:[0,1,1]
	v_pk_fma_f32 v[2:3], v[136:137], v[2:3], v[6:7] op_sel:[0,0,1] op_sel_hi:[0,1,0]
	v_pk_fma_f32 v[4:5], v[142:143], v[0:1], v[24:25] op_sel:[0,1,0] op_sel_hi:[1,0,1]
	v_pk_fma_f32 v[6:7], v[138:139], v[2:3], v[10:11] op_sel:[0,1,0] op_sel_hi:[1,0,1]
	s_waitcnt lgkmcnt(2)
	v_lshlrev_b32_e32 v161, 16, v16
	v_and_b32_e32 v160, 0xffff0000, v16
	v_pk_fma_f32 v[0:1], v[140:141], v[0:1], v[4:5] op_sel_hi:[0,1,1]
	v_pk_fma_f32 v[2:3], v[136:137], v[2:3], v[6:7] op_sel_hi:[0,1,1]
	v_pk_fma_f32 v[4:5], v[142:143], v[0:1], v[160:161] op_sel:[0,1,0] op_sel_hi:[1,0,1]
	v_pk_fma_f32 v[6:7], v[138:139], v[2:3], v[12:13] op_sel:[0,1,0] op_sel_hi:[1,0,1]
	v_lshlrev_b32_e32 v165, 16, v17
	v_and_b32_e32 v164, 0xffff0000, v17
	v_pk_fma_f32 v[0:1], v[140:141], v[0:1], v[4:5] op_sel_hi:[0,1,1]
	v_pk_fma_f32 v[2:3], v[136:137], v[2:3], v[6:7] op_sel_hi:[0,1,1]
	ds_read2_b32 v[30:31], v212 offset0:40 offset1:108
	v_pk_fma_f32 v[4:5], v[142:143], v[0:1], v[164:165] op_sel:[0,1,0] op_sel_hi:[1,0,1]
	v_pk_fma_f32 v[6:7], v[138:139], v[2:3], v[14:15] op_sel:[0,1,0] op_sel_hi:[1,0,1]
	s_waitcnt lgkmcnt(2)
	v_lshlrev_b32_e32 v163, 16, v26
	v_and_b32_e32 v162, 0xffff0000, v26
	v_lshlrev_b32_e32 v17, 16, v27
	v_and_b32_e32 v16, 0xffff0000, v27
	s_waitcnt lgkmcnt(1)
	v_lshlrev_b32_e32 v27, 16, v28
	v_and_b32_e32 v26, 0xffff0000, v28
	v_pk_fma_f32 v[0:1], v[140:141], v[0:1], v[4:5] op_sel_hi:[0,1,1]
	v_pk_fma_f32 v[2:3], v[136:137], v[2:3], v[6:7] op_sel_hi:[0,1,1]
	ds_read2_b32 v[152:153], v213 offset0:48 offset1:116
	ds_read2_b32 v[154:155], v212 offset0:176 offset1:244
	ds_read2_b32 v[156:157], v213 offset0:184 offset1:252
	v_pk_fma_f32 v[4:5], v[142:143], v[0:1], v[26:27] op_sel:[0,1,0] op_sel_hi:[1,0,1]
	v_pk_fma_f32 v[6:7], v[138:139], v[2:3], v[162:163] op_sel:[0,1,0] op_sel_hi:[1,0,1]
	v_lshlrev_b32_e32 v169, 16, v29
	v_and_b32_e32 v168, 0xffff0000, v29
	v_pk_fma_f32 v[0:1], v[140:141], v[0:1], v[4:5] op_sel_hi:[0,1,1]
	v_pk_fma_f32 v[2:3], v[136:137], v[2:3], v[6:7] op_sel_hi:[0,1,1]
	v_pk_fma_f32 v[4:5], v[142:143], v[0:1], v[168:169] op_sel:[0,1,0] op_sel_hi:[1,0,1]
	v_pk_fma_f32 v[6:7], v[138:139], v[2:3], v[16:17] op_sel:[0,1,0] op_sel_hi:[1,0,1]
	s_waitcnt lgkmcnt(3)
	v_lshlrev_b32_e32 v167, 16, v30
	v_and_b32_e32 v166, 0xffff0000, v30
	v_lshlrev_b32_e32 v29, 16, v31
	v_and_b32_e32 v28, 0xffff0000, v31
	s_waitcnt lgkmcnt(2)
	v_lshlrev_b32_e32 v31, 16, v152
	v_and_b32_e32 v30, 0xffff0000, v152
	v_pk_fma_f32 v[0:1], v[140:141], v[0:1], v[4:5] op_sel_hi:[0,1,1]
	v_pk_fma_f32 v[2:3], v[136:137], v[2:3], v[6:7] op_sel_hi:[0,1,1]
	v_pk_fma_f32 v[4:5], v[142:143], v[0:1], v[30:31] op_sel:[0,1,0] op_sel_hi:[1,0,1]
	v_pk_fma_f32 v[6:7], v[138:139], v[2:3], v[166:167] op_sel:[0,1,0] op_sel_hi:[1,0,1]
	v_lshlrev_b32_e32 v152, 16, v153
	v_and_b32_e32 v153, 0xffff0000, v153
	v_pk_fma_f32 v[0:1], v[140:141], v[0:1], v[4:5] op_sel_hi:[0,1,1]
	v_pk_fma_f32 v[2:3], v[136:137], v[2:3], v[6:7] op_sel_hi:[0,1,1]
	v_pk_fma_f32 v[4:5], v[150:151], v[0:1], v[152:153]
	v_pk_fma_f32 v[6:7], v[138:139], v[2:3], v[28:29] op_sel:[0,1,0] op_sel_hi:[1,0,1]
	ds_read2_b32 v[16:17], v202 offset0:64 offset1:132
	s_waitcnt lgkmcnt(2)
	v_lshlrev_b32_e32 v171, 16, v154
	v_and_b32_e32 v170, 0xffff0000, v154
	v_pk_fma_f32 v[2:3], v[136:137], v[2:3], v[6:7] op_sel_hi:[0,1,1]
	s_waitcnt lgkmcnt(1)
	v_lshlrev_b32_e32 v12, 16, v156
	v_and_b32_e32 v13, 0xffff0000, v156
	v_pk_fma_f32 v[0:1], v[140:141], v[0:1], v[4:5] op_sel:[0,0,1] op_sel_hi:[0,1,0]
	v_pk_fma_f32 v[6:7], v[138:139], v[2:3], v[170:171] op_sel:[0,1,0] op_sel_hi:[1,0,1]
	v_pk_fma_f32 v[4:5], v[150:151], v[0:1], v[12:13]
	v_lshlrev_b32_e32 v18, 16, v155
	v_and_b32_e32 v19, 0xffff0000, v155
	v_pk_fma_f32 v[2:3], v[136:137], v[2:3], v[6:7] op_sel_hi:[0,1,1]
	v_lshlrev_b32_e32 v15, 16, v157
	v_and_b32_e32 v14, 0xffff0000, v157
	v_pk_fma_f32 v[0:1], v[140:141], v[0:1], v[4:5] op_sel:[0,0,1] op_sel_hi:[0,1,0]
	v_pk_fma_f32 v[6:7], v[148:149], v[2:3], v[18:19]
	ds_read2_b32 v[18:19], v203 offset0:64 offset1:132
	ds_read2_b32 v[20:21], v204 offset0:72 offset1:140
	v_pk_fma_f32 v[4:5], v[142:143], v[0:1], v[14:15] op_sel:[0,1,0] op_sel_hi:[1,0,1]
	s_waitcnt lgkmcnt(2)
	v_lshlrev_b32_e32 v153, 16, v16
	v_and_b32_e32 v152, 0xffff0000, v16
	v_pk_fma_f32 v[0:1], v[140:141], v[0:1], v[4:5] op_sel_hi:[0,1,1]
	ds_read2_b32 v[158:159], v214 offset0:56 offset1:124
	v_pk_fma_f32 v[4:5], v[142:143], v[0:1], v[152:153] op_sel:[0,1,0] op_sel_hi:[1,0,1]
	v_lshlrev_b32_e32 v157, 16, v17
	v_and_b32_e32 v156, 0xffff0000, v17
	v_pk_fma_f32 v[0:1], v[140:141], v[0:1], v[4:5] op_sel_hi:[0,1,1]
	ds_read2_b32 v[22:23], v205 offset0:72 offset1:140
	ds_read2_b32 v[24:25], v206 offset0:80 offset1:148
	v_pk_fma_f32 v[4:5], v[142:143], v[0:1], v[156:157] op_sel:[0,1,0] op_sel_hi:[1,0,1]
	s_waitcnt lgkmcnt(4)
	v_lshlrev_b32_e32 v155, 16, v18
	v_and_b32_e32 v154, 0xffff0000, v18
	v_lshlrev_b32_e32 v17, 16, v19
	v_and_b32_e32 v16, 0xffff0000, v19
	s_waitcnt lgkmcnt(3)
	v_lshlrev_b32_e32 v19, 16, v20
	v_and_b32_e32 v18, 0xffff0000, v20
	v_pk_fma_f32 v[0:1], v[140:141], v[0:1], v[4:5] op_sel_hi:[0,1,1]
	v_pk_fma_f32 v[4:5], v[142:143], v[0:1], v[18:19] op_sel:[0,1,0] op_sel_hi:[1,0,1]
	s_waitcnt lgkmcnt(2)
	v_lshlrev_b32_e32 v8, 16, v158
	v_and_b32_e32 v9, 0xffff0000, v158
	v_lshlrev_b32_e32 v11, 16, v159
	v_and_b32_e32 v10, 0xffff0000, v159
	v_lshlrev_b32_e32 v159, 16, v21
	v_and_b32_e32 v158, 0xffff0000, v21
	v_pk_fma_f32 v[0:1], v[140:141], v[0:1], v[4:5] op_sel_hi:[0,1,1]
	ds_read2_b32 v[26:27], v207 offset0:80 offset1:148
	ds_read2_b32 v[28:29], v208 offset0:88 offset1:156
	v_pk_fma_f32 v[4:5], v[142:143], v[0:1], v[158:159] op_sel:[0,1,0] op_sel_hi:[1,0,1]
	s_waitcnt lgkmcnt(3)
	v_lshlrev_b32_e32 v161, 16, v22
	v_and_b32_e32 v160, 0xffff0000, v22
	v_lshlrev_b32_e32 v21, 16, v23
	v_and_b32_e32 v20, 0xffff0000, v23
	s_waitcnt lgkmcnt(2)
	v_lshlrev_b32_e32 v23, 16, v24
	v_and_b32_e32 v22, 0xffff0000, v24
	v_pk_fma_f32 v[0:1], v[140:141], v[0:1], v[4:5] op_sel_hi:[0,1,1]
	v_pk_fma_f32 v[4:5], v[142:143], v[0:1], v[22:23] op_sel:[0,1,0] op_sel_hi:[1,0,1]
	v_lshlrev_b32_e32 v165, 16, v25
	v_and_b32_e32 v164, 0xffff0000, v25
	v_pk_fma_f32 v[0:1], v[140:141], v[0:1], v[4:5] op_sel_hi:[0,1,1]
	v_pk_fma_f32 v[4:5], v[142:143], v[0:1], v[164:165] op_sel:[0,1,0] op_sel_hi:[1,0,1]
	s_waitcnt lgkmcnt(1)
	v_lshlrev_b32_e32 v163, 16, v26
	v_and_b32_e32 v162, 0xffff0000, v26
	v_lshlrev_b32_e32 v25, 16, v27
	v_and_b32_e32 v24, 0xffff0000, v27
	s_waitcnt lgkmcnt(0)
	v_lshlrev_b32_e32 v27, 16, v28
	v_and_b32_e32 v26, 0xffff0000, v28
	v_pk_fma_f32 v[0:1], v[140:141], v[0:1], v[4:5] op_sel_hi:[0,1,1]
	v_pk_fma_f32 v[4:5], v[142:143], v[0:1], v[26:27] op_sel:[0,1,0] op_sel_hi:[1,0,1]
	v_pk_fma_f32 v[2:3], v[136:137], v[2:3], v[6:7] op_sel:[0,0,1] op_sel_hi:[0,1,0]
	v_pk_fma_f32 v[156:157], v[140:141], v[0:1], v[4:5] op_sel_hi:[0,1,1]
	v_pk_fma_f32 v[4:5], v[148:149], v[2:3], v[8:9]
	ds_read2_b32 v[30:31], v209 offset0:88 offset1:156
	v_pk_fma_f32 v[2:3], v[136:137], v[2:3], v[4:5] op_sel:[0,0,1] op_sel_hi:[0,1,0]
	v_pk_fma_f32 v[4:5], v[138:139], v[2:3], v[10:11] op_sel:[0,1,0] op_sel_hi:[1,0,1]
	ds_read2_b32 v[6:7], v197 offset0:104 offset1:172
	v_pk_fma_f32 v[2:3], v[136:137], v[2:3], v[4:5] op_sel_hi:[0,1,1]
	v_pk_fma_f32 v[4:5], v[138:139], v[2:3], v[154:155] op_sel:[0,1,0] op_sel_hi:[1,0,1]
	s_waitcnt lgkmcnt(1)
	v_lshlrev_b32_e32 v167, 16, v30
	v_pk_fma_f32 v[2:3], v[136:137], v[2:3], v[4:5] op_sel_hi:[0,1,1]
	v_pk_fma_f32 v[4:5], v[138:139], v[2:3], v[16:17] op_sel:[0,1,0] op_sel_hi:[1,0,1]
	v_and_b32_e32 v166, 0xffff0000, v30
	v_pk_fma_f32 v[2:3], v[136:137], v[2:3], v[4:5] op_sel_hi:[0,1,1]
	v_pk_fma_f32 v[4:5], v[138:139], v[2:3], v[160:161] op_sel:[0,1,0] op_sel_hi:[1,0,1]
	v_lshlrev_b32_e32 v0, 16, v31
	v_pk_fma_f32 v[2:3], v[136:137], v[2:3], v[4:5] op_sel_hi:[0,1,1]
	v_pk_fma_f32 v[4:5], v[138:139], v[2:3], v[20:21] op_sel:[0,1,0] op_sel_hi:[1,0,1]
	v_and_b32_e32 v1, 0xffff0000, v31
	v_pk_fma_f32 v[2:3], v[136:137], v[2:3], v[4:5] op_sel_hi:[0,1,1]
	v_pk_fma_f32 v[4:5], v[138:139], v[2:3], v[162:163] op_sel:[0,1,0] op_sel_hi:[1,0,1]
	ds_read2_b32 v[8:9], v198 offset0:112 offset1:180
	v_pk_fma_f32 v[2:3], v[136:137], v[2:3], v[4:5] op_sel_hi:[0,1,1]
	v_pk_fma_f32 v[4:5], v[138:139], v[2:3], v[24:25] op_sel:[0,1,0] op_sel_hi:[1,0,1]
	ds_read2_b32 v[10:11], v199 offset0:112 offset1:180
	v_pk_fma_f32 v[2:3], v[136:137], v[2:3], v[4:5] op_sel_hi:[0,1,1]
	v_pk_fma_f32 v[4:5], v[138:139], v[2:3], v[166:167] op_sel:[0,1,0] op_sel_hi:[1,0,1]
	ds_read2_b32 v[12:13], v200 offset0:120 offset1:188
	v_pk_fma_f32 v[152:153], v[136:137], v[2:3], v[4:5] op_sel_hi:[0,1,1]
	v_pk_fma_f32 v[154:155], v[148:149], v[152:153], v[0:1]
	ds_read2_b32 v[0:1], v194 offset0:96 offset1:164
	ds_read2_b32 v[2:3], v195 offset0:96 offset1:164
	ds_read2_b32 v[4:5], v196 offset0:104 offset1:172
	ds_read2_b32 v[14:15], v201 offset0:120 offset1:188
	v_lshlrev_b32_e32 v28, 16, v29
	v_and_b32_e32 v29, 0xffff0000, v29
	s_waitcnt lgkmcnt(3)
	v_lshlrev_b32_e32 v176, 16, v0
	v_and_b32_e32 v177, 0xffff0000, v0
	s_waitcnt lgkmcnt(2)
	v_lshlrev_b32_e32 v160, 16, v2
	v_and_b32_e32 v161, 0xffff0000, v2
	v_lshlrev_b32_e32 v179, 16, v1
	v_and_b32_e32 v178, 0xffff0000, v1
	v_lshlrev_b32_e32 v163, 16, v3
	v_and_b32_e32 v162, 0xffff0000, v3
	s_waitcnt lgkmcnt(1)
	v_lshlrev_b32_e32 v181, 16, v4
	v_and_b32_e32 v180, 0xffff0000, v4
	v_lshlrev_b32_e32 v165, 16, v6
	v_and_b32_e32 v164, 0xffff0000, v6
	v_lshlrev_b32_e32 v183, 16, v5
	v_and_b32_e32 v182, 0xffff0000, v5
	v_lshlrev_b32_e32 v167, 16, v7
	v_and_b32_e32 v166, 0xffff0000, v7
	v_lshlrev_b32_e32 v185, 16, v8
	v_and_b32_e32 v184, 0xffff0000, v8
	v_lshlrev_b32_e32 v169, 16, v10
	v_and_b32_e32 v168, 0xffff0000, v10
	v_lshlrev_b32_e32 v187, 16, v9
	v_and_b32_e32 v186, 0xffff0000, v9
	v_lshlrev_b32_e32 v171, 16, v11
	v_and_b32_e32 v170, 0xffff0000, v11
	v_lshlrev_b32_e32 v189, 16, v12
	v_and_b32_e32 v188, 0xffff0000, v12
	s_waitcnt lgkmcnt(0)
	v_lshlrev_b32_e32 v173, 16, v14
	v_and_b32_e32 v172, 0xffff0000, v14
	v_lshlrev_b32_e32 v191, 16, v13
	v_and_b32_e32 v190, 0xffff0000, v13
	v_lshlrev_b32_e32 v175, 16, v15
	v_and_b32_e32 v174, 0xffff0000, v15
	v_mfma_f32_32x32x16_bf16 v[0:15], v[84:87], v[222:225], 0
	v_fma_f32 v158, v150, v156, v28
	v_fma_f32 v159, v151, v157, v29
	s_waitcnt lgkmcnt(0)
	v_mfma_f32_32x32x16_bf16 v[16:31], v[80:83], v[230:233], 0
	s_nop 8
	v_cvt_pk_bf16_f32 v0, v0, v1
	v_cvt_pk_bf16_f32 v1, v2, v3
	v_cvt_pk_bf16_f32 v4, v4, v5
	v_cvt_pk_bf16_f32 v5, v6, v7
	ds_write2_b64 v125, v[0:1], v[4:5] offset1:2
	v_cvt_pk_bf16_f32 v4, v12, v13
	v_cvt_pk_bf16_f32 v5, v14, v15
	v_cvt_pk_bf16_f32 v2, v16, v17
	v_cvt_pk_bf16_f32 v3, v18, v19
	v_cvt_pk_bf16_f32 v0, v20, v21
	v_cvt_pk_bf16_f32 v1, v22, v23
	ds_write2_b64 v192, v[2:3], v[0:1] offset0:64 offset1:66
	v_cvt_pk_bf16_f32 v0, v8, v9
	v_cvt_pk_bf16_f32 v1, v10, v11
	v_cvt_pk_bf16_f32 v2, v24, v25
	v_cvt_pk_bf16_f32 v3, v26, v27
	ds_write2_b64 v125, v[0:1], v[4:5] offset0:4 offset1:6
	v_cvt_pk_bf16_f32 v0, v28, v29
	v_cvt_pk_bf16_f32 v1, v30, v31
	ds_write2_b64 v192, v[2:3], v[0:1] offset0:68 offset1:70
	v_mfma_f32_32x32x16_bf16 v[0:15], v[76:79], v[222:225], 0
	v_mfma_f32_32x32x16_bf16 v[16:31], v[72:75], v[230:233], 0
	s_nop 10
	v_cvt_pk_bf16_f32 v0, v0, v1
	v_cvt_pk_bf16_f32 v1, v2, v3
	v_cvt_pk_bf16_f32 v4, v4, v5
	v_cvt_pk_bf16_f32 v5, v6, v7
	ds_write2_b64 v125, v[0:1], v[4:5] offset0:8 offset1:10
	v_cvt_pk_bf16_f32 v4, v12, v13
	v_cvt_pk_bf16_f32 v5, v14, v15
	v_cvt_pk_bf16_f32 v2, v16, v17
	v_cvt_pk_bf16_f32 v3, v18, v19
	v_cvt_pk_bf16_f32 v0, v20, v21
	v_cvt_pk_bf16_f32 v1, v22, v23
	ds_write2_b64 v192, v[2:3], v[0:1] offset0:72 offset1:74
	v_cvt_pk_bf16_f32 v0, v8, v9
	v_cvt_pk_bf16_f32 v1, v10, v11
	v_cvt_pk_bf16_f32 v2, v24, v25
	v_cvt_pk_bf16_f32 v3, v26, v27
	ds_write2_b64 v125, v[0:1], v[4:5] offset0:12 offset1:14
	v_cvt_pk_bf16_f32 v0, v28, v29
	v_cvt_pk_bf16_f32 v1, v30, v31
	ds_write2_b64 v192, v[2:3], v[0:1] offset0:76 offset1:78
	v_mfma_f32_32x32x16_bf16 v[0:15], v[68:71], v[222:225], 0
	v_mfma_f32_32x32x16_bf16 v[16:31], v[64:67], v[230:233], 0
	s_nop 10
	v_cvt_pk_bf16_f32 v0, v0, v1
	v_cvt_pk_bf16_f32 v1, v2, v3
	v_cvt_pk_bf16_f32 v4, v4, v5
	v_cvt_pk_bf16_f32 v5, v6, v7
	ds_write2_b64 v125, v[0:1], v[4:5] offset0:16 offset1:18
	v_cvt_pk_bf16_f32 v4, v12, v13
	v_cvt_pk_bf16_f32 v5, v14, v15
	v_cvt_pk_bf16_f32 v2, v16, v17
	v_cvt_pk_bf16_f32 v3, v18, v19
	v_cvt_pk_bf16_f32 v0, v20, v21
	v_cvt_pk_bf16_f32 v1, v22, v23
	ds_write2_b64 v192, v[2:3], v[0:1] offset0:80 offset1:82
	v_cvt_pk_bf16_f32 v0, v8, v9
	v_cvt_pk_bf16_f32 v1, v10, v11
	v_cvt_pk_bf16_f32 v2, v24, v25
	v_cvt_pk_bf16_f32 v3, v26, v27
	ds_write2_b64 v125, v[0:1], v[4:5] offset0:20 offset1:22
	v_cvt_pk_bf16_f32 v0, v28, v29
	v_cvt_pk_bf16_f32 v1, v30, v31
	ds_write2_b64 v192, v[2:3], v[0:1] offset0:84 offset1:86
	v_mfma_f32_32x32x16_bf16 v[0:15], v[60:63], v[222:225], 0
	v_mfma_f32_32x32x16_bf16 v[16:31], v[56:59], v[230:233], 0
	s_nop 10
	v_cvt_pk_bf16_f32 v0, v0, v1
	v_cvt_pk_bf16_f32 v1, v2, v3
	v_cvt_pk_bf16_f32 v4, v4, v5
	v_cvt_pk_bf16_f32 v5, v6, v7
	ds_write2_b64 v125, v[0:1], v[4:5] offset0:24 offset1:26
	v_cvt_pk_bf16_f32 v4, v12, v13
	v_cvt_pk_bf16_f32 v5, v14, v15
	v_cvt_pk_bf16_f32 v3, v18, v19
	v_pk_fma_f32 v[18:19], v[140:141], v[156:157], v[158:159] op_sel:[0,0,1] op_sel_hi:[0,1,0]
	v_cvt_pk_bf16_f32 v0, v20, v21
	v_pk_fma_f32 v[20:21], v[150:151], v[18:19], v[176:177]
	v_cvt_pk_bf16_f32 v2, v16, v17
	v_pk_fma_f32 v[18:19], v[140:141], v[18:19], v[20:21] op_sel:[0,0,1] op_sel_hi:[0,1,0]
	v_pk_fma_f32 v[20:21], v[142:143], v[18:19], v[178:179] op_sel:[0,1,0] op_sel_hi:[1,0,1]
	v_cvt_pk_bf16_f32 v1, v22, v23
	v_pk_fma_f32 v[18:19], v[140:141], v[18:19], v[20:21] op_sel_hi:[0,1,1]
	v_pk_fma_f32 v[20:21], v[142:143], v[18:19], v[180:181] op_sel:[0,1,0] op_sel_hi:[1,0,1]
	ds_write2_b64 v192, v[2:3], v[0:1] offset0:88 offset1:90
	v_pk_fma_f32 v[18:19], v[140:141], v[18:19], v[20:21] op_sel_hi:[0,1,1]
	v_pk_fma_f32 v[20:21], v[142:143], v[18:19], v[182:183] op_sel:[0,1,0] op_sel_hi:[1,0,1]
	v_cvt_pk_bf16_f32 v2, v8, v9
	v_pk_fma_f32 v[18:19], v[140:141], v[18:19], v[20:21] op_sel_hi:[0,1,1]
	v_pk_fma_f32 v[20:21], v[142:143], v[18:19], v[184:185] op_sel:[0,1,0] op_sel_hi:[1,0,1]
	v_cvt_pk_bf16_f32 v3, v10, v11
	v_pk_fma_f32 v[18:19], v[140:141], v[18:19], v[20:21] op_sel_hi:[0,1,1]
	v_pk_fma_f32 v[20:21], v[142:143], v[18:19], v[186:187] op_sel:[0,1,0] op_sel_hi:[1,0,1]
	v_cvt_pk_bf16_f32 v0, v24, v25
	v_pk_fma_f32 v[18:19], v[140:141], v[18:19], v[20:21] op_sel_hi:[0,1,1]
	v_cvt_pk_bf16_f32 v1, v26, v27
	ds_write2_b64 v125, v[2:3], v[4:5] offset0:28 offset1:30
	v_cvt_pk_bf16_f32 v2, v28, v29
	v_cvt_pk_bf16_f32 v3, v30, v31
	v_pk_fma_f32 v[20:21], v[142:143], v[18:19], v[188:189] op_sel:[0,1,0] op_sel_hi:[1,0,1]
	ds_write2_b64 v192, v[0:1], v[2:3] offset0:92 offset1:94
	v_pk_fma_f32 v[18:19], v[140:141], v[18:19], v[20:21] op_sel_hi:[0,1,1]
	s_waitcnt lgkmcnt(0)
	v_pk_fma_f32 v[20:21], v[142:143], v[18:19], v[190:191] op_sel:[0,1,0] op_sel_hi:[1,0,1]
	ds_read2_b32 v[14:15], v145 offset1:68
	ds_read2_b32 v[12:13], v215 offset0:128 offset1:196
	ds_read2_b32 v[10:11], v145 offset0:136 offset1:204
	ds_read2_b32 v[8:9], v216 offset0:8 offset1:76
	ds_read2_b32 v[6:7], v217 offset0:16 offset1:84
	ds_read2_b32 v[4:5], v216 offset0:144 offset1:212
	ds_read2_b32 v[2:3], v217 offset0:152 offset1:220
	ds_read2_b32 v[0:1], v210 offset0:24 offset1:92
	s_waitcnt lgkmcnt(7)
	v_lshlrev_b32_e32 v17, 16, v14
	v_and_b32_e32 v16, 0xffff0000, v14
	v_pk_fma_f32 v[18:19], v[140:141], v[18:19], v[20:21] op_sel_hi:[0,1,1]
	v_pk_fma_f32 v[16:17], v[142:143], v[18:19], v[16:17] op_sel:[0,1,0] op_sel_hi:[1,0,1]
	v_lshlrev_b32_e32 v14, 16, v15
	v_and_b32_e32 v15, 0xffff0000, v15
	v_pk_fma_f32 v[18:19], v[140:141], v[18:19], v[16:17] op_sel_hi:[0,1,1]
	s_waitcnt lgkmcnt(6)
	v_lshlrev_b32_e32 v23, 16, v12
	v_and_b32_e32 v22, 0xffff0000, v12
	v_pk_fma_f32 v[20:21], v[150:151], v[18:19], v[14:15]
	v_lshlrev_b32_e32 v14, 16, v13
	v_and_b32_e32 v15, 0xffff0000, v13
	v_pk_fma_f32 v[12:13], v[136:137], v[152:153], v[154:155] op_sel:[0,0,1] op_sel_hi:[0,1,0]
	v_pk_fma_f32 v[16:17], v[148:149], v[12:13], v[160:161]
	s_waitcnt lgkmcnt(5)
	v_lshlrev_b32_e32 v24, 16, v10
	v_pk_fma_f32 v[12:13], v[136:137], v[12:13], v[16:17] op_sel:[0,0,1] op_sel_hi:[0,1,0]
	v_pk_fma_f32 v[16:17], v[138:139], v[12:13], v[162:163] op_sel:[0,1,0] op_sel_hi:[1,0,1]
	v_and_b32_e32 v25, 0xffff0000, v10
	v_pk_fma_f32 v[12:13], v[136:137], v[12:13], v[16:17] op_sel_hi:[0,1,1]
	v_pk_fma_f32 v[16:17], v[138:139], v[12:13], v[164:165] op_sel:[0,1,0] op_sel_hi:[1,0,1]
	v_pk_fma_f32 v[18:19], v[140:141], v[18:19], v[20:21] op_sel:[0,0,1] op_sel_hi:[0,1,0]
	v_pk_fma_f32 v[12:13], v[136:137], v[12:13], v[16:17] op_sel_hi:[0,1,1]
	v_pk_fma_f32 v[16:17], v[138:139], v[12:13], v[166:167] op_sel:[0,1,0] op_sel_hi:[1,0,1]
	v_pk_fma_f32 v[20:21], v[150:151], v[18:19], v[24:25]
	v_pk_fma_f32 v[12:13], v[136:137], v[12:13], v[16:17] op_sel_hi:[0,1,1]
	v_pk_fma_f32 v[16:17], v[138:139], v[12:13], v[168:169] op_sel:[0,1,0] op_sel_hi:[1,0,1]
	v_lshlrev_b32_e32 v29, 16, v11
	v_pk_fma_f32 v[12:13], v[136:137], v[12:13], v[16:17] op_sel_hi:[0,1,1]
	v_pk_fma_f32 v[16:17], v[138:139], v[12:13], v[170:171] op_sel:[0,1,0] op_sel_hi:[1,0,1]
	v_and_b32_e32 v28, 0xffff0000, v11
	v_pk_fma_f32 v[12:13], v[136:137], v[12:13], v[16:17] op_sel_hi:[0,1,1]
	v_pk_fma_f32 v[16:17], v[138:139], v[12:13], v[172:173] op_sel:[0,1,0] op_sel_hi:[1,0,1]
	v_pk_fma_f32 v[18:19], v[140:141], v[18:19], v[20:21] op_sel:[0,0,1] op_sel_hi:[0,1,0]
	v_pk_fma_f32 v[12:13], v[136:137], v[12:13], v[16:17] op_sel_hi:[0,1,1]
	v_pk_fma_f32 v[16:17], v[138:139], v[12:13], v[174:175] op_sel:[0,1,0] op_sel_hi:[1,0,1]
	v_pk_fma_f32 v[20:21], v[142:143], v[18:19], v[28:29] op_sel:[0,1,0] op_sel_hi:[1,0,1]
	v_pk_fma_f32 v[12:13], v[136:137], v[12:13], v[16:17] op_sel_hi:[0,1,1]
	v_pk_fma_f32 v[16:17], v[138:139], v[12:13], v[22:23] op_sel:[0,1,0] op_sel_hi:[1,0,1]
	s_waitcnt lgkmcnt(3)
	v_lshlrev_b32_e32 v49, 16, v6
	v_pk_fma_f32 v[12:13], v[136:137], v[12:13], v[16:17] op_sel_hi:[0,1,1]
	v_pk_fma_f32 v[14:15], v[148:149], v[12:13], v[14:15]
	v_and_b32_e32 v48, 0xffff0000, v6
	v_pk_fma_f32 v[18:19], v[140:141], v[18:19], v[20:21] op_sel_hi:[0,1,1]
	v_lshlrev_b32_e32 v26, 16, v8
	v_and_b32_e32 v27, 0xffff0000, v8
	v_pk_fma_f32 v[20:21], v[142:143], v[18:19], v[48:49] op_sel:[0,1,0] op_sel_hi:[1,0,1]
	v_pk_fma_f32 v[12:13], v[136:137], v[12:13], v[14:15] op_sel:[0,0,1] op_sel_hi:[0,1,0]
	v_lshlrev_b32_e32 v53, 16, v7
	v_and_b32_e32 v52, 0xffff0000, v7
	v_pk_fma_f32 v[18:19], v[140:141], v[18:19], v[20:21] op_sel_hi:[0,1,1]
	v_pk_fma_f32 v[14:15], v[148:149], v[12:13], v[26:27]
	v_lshlrev_b32_e32 v31, 16, v9
	v_and_b32_e32 v30, 0xffff0000, v9
	v_pk_fma_f32 v[20:21], v[142:143], v[18:19], v[52:53] op_sel:[0,1,0] op_sel_hi:[1,0,1]
	v_pk_fma_f32 v[12:13], v[136:137], v[12:13], v[14:15] op_sel:[0,0,1] op_sel_hi:[0,1,0]
	s_waitcnt lgkmcnt(2)
	v_lshlrev_b32_e32 v51, 16, v4
	v_and_b32_e32 v50, 0xffff0000, v4
	v_lshlrev_b32_e32 v7, 16, v5
	v_and_b32_e32 v6, 0xffff0000, v5
	s_waitcnt lgkmcnt(1)
	v_lshlrev_b32_e32 v5, 16, v2
	v_and_b32_e32 v4, 0xffff0000, v2
	v_pk_fma_f32 v[18:19], v[140:141], v[18:19], v[20:21] op_sel_hi:[0,1,1]
	v_pk_fma_f32 v[14:15], v[138:139], v[12:13], v[30:31] op_sel:[0,1,0] op_sel_hi:[1,0,1]
	v_pk_fma_f32 v[4:5], v[142:143], v[18:19], v[4:5] op_sel:[0,1,0] op_sel_hi:[1,0,1]
	v_pk_fma_f32 v[12:13], v[136:137], v[12:13], v[14:15] op_sel_hi:[0,1,1]
	v_lshlrev_b32_e32 v57, 16, v3
	v_and_b32_e32 v56, 0xffff0000, v3
	v_pk_fma_f32 v[4:5], v[140:141], v[18:19], v[4:5] op_sel_hi:[0,1,1]
	v_pk_fma_f32 v[14:15], v[138:139], v[12:13], v[50:51] op_sel:[0,1,0] op_sel_hi:[1,0,1]
	v_pk_fma_f32 v[18:19], v[142:143], v[4:5], v[56:57] op_sel:[0,1,0] op_sel_hi:[1,0,1]
	v_pk_fma_f32 v[12:13], v[136:137], v[12:13], v[14:15] op_sel_hi:[0,1,1]
	s_waitcnt lgkmcnt(0)
	v_lshlrev_b32_e32 v55, 16, v0
	v_and_b32_e32 v54, 0xffff0000, v0
	v_lshlrev_b32_e32 v3, 16, v1
	v_and_b32_e32 v2, 0xffff0000, v1
	ds_read2_b32 v[0:1], v211 offset0:32 offset1:100
	ds_read2_b32 v[58:59], v210 offset0:160 offset1:228
	ds_read2_b32 v[60:61], v211 offset0:168 offset1:236
	ds_read2_b32 v[62:63], v212 offset0:40 offset1:108
	ds_read2_b32 v[22:23], v213 offset0:48 offset1:116
	ds_read2_b32 v[16:17], v212 offset0:176 offset1:244
	ds_read2_b32 v[10:11], v213 offset0:184 offset1:252
	ds_read2_b32 v[8:9], v214 offset0:56 offset1:124
	s_waitcnt lgkmcnt(7)
	v_lshlrev_b32_e32 v65, 16, v0
	v_and_b32_e32 v64, 0xffff0000, v0
	v_pk_fma_f32 v[4:5], v[140:141], v[4:5], v[18:19] op_sel_hi:[0,1,1]
	v_pk_fma_f32 v[6:7], v[138:139], v[12:13], v[6:7] op_sel:[0,1,0] op_sel_hi:[1,0,1]
	v_pk_fma_f32 v[18:19], v[142:143], v[4:5], v[64:65] op_sel:[0,1,0] op_sel_hi:[1,0,1]
	v_pk_fma_f32 v[6:7], v[136:137], v[12:13], v[6:7] op_sel_hi:[0,1,1]
	v_lshlrev_b32_e32 v69, 16, v1
	v_and_b32_e32 v68, 0xffff0000, v1
	v_pk_fma_f32 v[4:5], v[140:141], v[4:5], v[18:19] op_sel_hi:[0,1,1]
	v_pk_fma_f32 v[12:13], v[138:139], v[6:7], v[54:55] op_sel:[0,1,0] op_sel_hi:[1,0,1]
	v_pk_fma_f32 v[18:19], v[142:143], v[4:5], v[68:69] op_sel:[0,1,0] op_sel_hi:[1,0,1]
	v_pk_fma_f32 v[6:7], v[136:137], v[6:7], v[12:13] op_sel_hi:[0,1,1]
	s_waitcnt lgkmcnt(5)
	v_lshlrev_b32_e32 v1, 16, v60
	v_and_b32_e32 v0, 0xffff0000, v60
	v_pk_fma_f32 v[4:5], v[140:141], v[4:5], v[18:19] op_sel_hi:[0,1,1]
	v_pk_fma_f32 v[2:3], v[138:139], v[6:7], v[2:3] op_sel:[0,1,0] op_sel_hi:[1,0,1]
	v_lshlrev_b32_e32 v67, 16, v58
	v_and_b32_e32 v66, 0xffff0000, v58
	v_pk_fma_f32 v[0:1], v[142:143], v[4:5], v[0:1] op_sel:[0,1,0] op_sel_hi:[1,0,1]
	v_pk_fma_f32 v[2:3], v[136:137], v[6:7], v[2:3] op_sel_hi:[0,1,1]
	v_lshlrev_b32_e32 v60, 16, v61
	v_and_b32_e32 v61, 0xffff0000, v61
	v_pk_fma_f32 v[0:1], v[140:141], v[4:5], v[0:1] op_sel_hi:[0,1,1]
	v_pk_fma_f32 v[6:7], v[138:139], v[2:3], v[66:67] op_sel:[0,1,0] op_sel_hi:[1,0,1]
	v_lshlrev_b32_e32 v71, 16, v59
	v_and_b32_e32 v70, 0xffff0000, v59
	v_pk_fma_f32 v[4:5], v[150:151], v[0:1], v[60:61]
	v_pk_fma_f32 v[2:3], v[136:137], v[2:3], v[6:7] op_sel_hi:[0,1,1]
	v_pk_fma_f32 v[6:7], v[138:139], v[2:3], v[70:71] op_sel:[0,1,0] op_sel_hi:[1,0,1]
	s_waitcnt lgkmcnt(3)
	v_lshlrev_b32_e32 v14, 16, v22
	v_and_b32_e32 v15, 0xffff0000, v22
	v_pk_fma_f32 v[0:1], v[140:141], v[0:1], v[4:5] op_sel:[0,0,1] op_sel_hi:[0,1,0]
	v_lshlrev_b32_e32 v59, 16, v62
	v_and_b32_e32 v58, 0xffff0000, v62
	v_pk_fma_f32 v[2:3], v[136:137], v[2:3], v[6:7] op_sel_hi:[0,1,1]
	v_pk_fma_f32 v[4:5], v[150:151], v[0:1], v[14:15]
	v_pk_fma_f32 v[6:7], v[138:139], v[2:3], v[58:59] op_sel:[0,1,0] op_sel_hi:[1,0,1]
	v_lshlrev_b32_e32 v21, 16, v23
	v_and_b32_e32 v20, 0xffff0000, v23
	v_pk_fma_f32 v[0:1], v[140:141], v[0:1], v[4:5] op_sel:[0,0,1] op_sel_hi:[0,1,0]
	v_lshlrev_b32_e32 v18, 16, v63
	v_and_b32_e32 v19, 0xffff0000, v63
	v_pk_fma_f32 v[2:3], v[136:137], v[2:3], v[6:7] op_sel_hi:[0,1,1]
	v_pk_fma_f32 v[4:5], v[142:143], v[0:1], v[20:21] op_sel:[0,1,0] op_sel_hi:[1,0,1]
	v_pk_fma_f32 v[6:7], v[148:149], v[2:3], v[18:19]
	s_waitcnt lgkmcnt(2)
	v_lshlrev_b32_e32 v18, 16, v16
	v_and_b32_e32 v19, 0xffff0000, v16
	v_lshlrev_b32_e32 v23, 16, v17
	v_and_b32_e32 v22, 0xffff0000, v17
	s_waitcnt lgkmcnt(1)
	v_lshlrev_b32_e32 v17, 16, v10
	v_and_b32_e32 v16, 0xffff0000, v10
	v_pk_fma_f32 v[0:1], v[140:141], v[0:1], v[4:5] op_sel_hi:[0,1,1]
	v_pk_fma_f32 v[4:5], v[142:143], v[0:1], v[16:17] op_sel:[0,1,0] op_sel_hi:[1,0,1]
	v_lshlrev_b32_e32 v27, 16, v11
	v_and_b32_e32 v26, 0xffff0000, v11
	v_pk_fma_f32 v[0:1], v[140:141], v[0:1], v[4:5] op_sel_hi:[0,1,1]
	v_pk_fma_f32 v[4:5], v[142:143], v[0:1], v[26:27] op_sel:[0,1,0] op_sel_hi:[1,0,1]
	s_waitcnt lgkmcnt(0)
	v_lshlrev_b32_e32 v25, 16, v8
	v_and_b32_e32 v24, 0xffff0000, v8
	v_lshlrev_b32_e32 v29, 16, v9
	v_and_b32_e32 v28, 0xffff0000, v9
	ds_read2_b32 v[8:9], v202 offset0:64 offset1:132
	ds_read2_b32 v[30:31], v203 offset0:64 offset1:132
	ds_read2_b32 v[48:49], v204 offset0:72 offset1:140
	ds_read2_b32 v[50:51], v205 offset0:72 offset1:140
	ds_read2_b32 v[52:53], v206 offset0:80 offset1:148
	ds_read2_b32 v[54:55], v207 offset0:80 offset1:148
	ds_read2_b32 v[12:13], v208 offset0:88 offset1:156
	ds_read2_b32 v[10:11], v209 offset0:88 offset1:156
	s_waitcnt lgkmcnt(7)
	v_lshlrev_b32_e32 v57, 16, v8
	v_and_b32_e32 v56, 0xffff0000, v8
	v_pk_fma_f32 v[0:1], v[140:141], v[0:1], v[4:5] op_sel_hi:[0,1,1]
	v_pk_fma_f32 v[4:5], v[142:143], v[0:1], v[56:57] op_sel:[0,1,0] op_sel_hi:[1,0,1]
	v_lshlrev_b32_e32 v61, 16, v9
	v_and_b32_e32 v60, 0xffff0000, v9
	v_pk_fma_f32 v[0:1], v[140:141], v[0:1], v[4:5] op_sel_hi:[0,1,1]
	v_pk_fma_f32 v[4:5], v[142:143], v[0:1], v[60:61] op_sel:[0,1,0] op_sel_hi:[1,0,1]
	s_waitcnt lgkmcnt(5)
	v_lshlrev_b32_e32 v9, 16, v48
	v_and_b32_e32 v8, 0xffff0000, v48
	v_pk_fma_f32 v[0:1], v[140:141], v[0:1], v[4:5] op_sel_hi:[0,1,1]
	v_pk_fma_f32 v[4:5], v[142:143], v[0:1], v[8:9] op_sel:[0,1,0] op_sel_hi:[1,0,1]
	v_lshlrev_b32_e32 v65, 16, v49
	v_and_b32_e32 v64, 0xffff0000, v49
	v_pk_fma_f32 v[0:1], v[140:141], v[0:1], v[4:5] op_sel_hi:[0,1,1]
	v_pk_fma_f32 v[4:5], v[142:143], v[0:1], v[64:65] op_sel:[0,1,0] op_sel_hi:[1,0,1]
	v_lshlrev_b32_e32 v59, 16, v30
	v_and_b32_e32 v58, 0xffff0000, v30
	v_lshlrev_b32_e32 v63, 16, v31
	v_and_b32_e32 v62, 0xffff0000, v31
	s_waitcnt lgkmcnt(4)
	v_lshlrev_b32_e32 v31, 16, v50
	v_and_b32_e32 v30, 0xffff0000, v50
	v_lshlrev_b32_e32 v49, 16, v51
	v_and_b32_e32 v48, 0xffff0000, v51
	s_waitcnt lgkmcnt(3)
	v_lshlrev_b32_e32 v51, 16, v52
	v_and_b32_e32 v50, 0xffff0000, v52
	v_pk_fma_f32 v[0:1], v[140:141], v[0:1], v[4:5] op_sel_hi:[0,1,1]
	v_pk_fma_f32 v[4:5], v[142:143], v[0:1], v[50:51] op_sel:[0,1,0] op_sel_hi:[1,0,1]
	s_waitcnt lgkmcnt(2)
	v_lshlrev_b32_e32 v67, 16, v54
	v_pk_fma_f32 v[4:5], v[140:141], v[0:1], v[4:5] op_sel_hi:[0,1,1]
	v_pk_fma_f32 v[0:1], v[136:137], v[2:3], v[6:7] op_sel:[0,0,1] op_sel_hi:[0,1,0]
	v_pk_fma_f32 v[2:3], v[148:149], v[0:1], v[18:19]
	v_and_b32_e32 v66, 0xffff0000, v54
	v_pk_fma_f32 v[0:1], v[136:137], v[0:1], v[2:3] op_sel:[0,0,1] op_sel_hi:[0,1,0]
	v_pk_fma_f32 v[2:3], v[138:139], v[0:1], v[22:23] op_sel:[0,1,0] op_sel_hi:[1,0,1]
	v_lshlrev_b32_e32 v52, 16, v53
	v_pk_fma_f32 v[0:1], v[136:137], v[0:1], v[2:3] op_sel_hi:[0,1,1]
	v_pk_fma_f32 v[2:3], v[138:139], v[0:1], v[24:25] op_sel:[0,1,0] op_sel_hi:[1,0,1]
	v_and_b32_e32 v53, 0xffff0000, v53
	v_pk_fma_f32 v[0:1], v[136:137], v[0:1], v[2:3] op_sel_hi:[0,1,1]
	v_pk_fma_f32 v[2:3], v[138:139], v[0:1], v[28:29] op_sel:[0,1,0] op_sel_hi:[1,0,1]
	v_pk_fma_f32 v[8:9], v[150:151], v[4:5], v[52:53]
	v_pk_fma_f32 v[0:1], v[136:137], v[0:1], v[2:3] op_sel_hi:[0,1,1]
	v_pk_fma_f32 v[2:3], v[138:139], v[0:1], v[58:59] op_sel:[0,1,0] op_sel_hi:[1,0,1]
	v_lshlrev_b32_e32 v14, 16, v55
	v_pk_fma_f32 v[0:1], v[136:137], v[0:1], v[2:3] op_sel_hi:[0,1,1]
	v_pk_fma_f32 v[2:3], v[138:139], v[0:1], v[62:63] op_sel:[0,1,0] op_sel_hi:[1,0,1]
	v_and_b32_e32 v15, 0xffff0000, v55
	v_pk_fma_f32 v[0:1], v[136:137], v[0:1], v[2:3] op_sel_hi:[0,1,1]
	v_pk_fma_f32 v[2:3], v[138:139], v[0:1], v[30:31] op_sel:[0,1,0] op_sel_hi:[1,0,1]
	v_pk_fma_f32 v[4:5], v[140:141], v[4:5], v[8:9] op_sel:[0,0,1] op_sel_hi:[0,1,0]
	v_pk_fma_f32 v[0:1], v[136:137], v[0:1], v[2:3] op_sel_hi:[0,1,1]
	v_pk_fma_f32 v[2:3], v[138:139], v[0:1], v[48:49] op_sel:[0,1,0] op_sel_hi:[1,0,1]
	s_waitcnt lgkmcnt(0)
	v_lshlrev_b32_e32 v6, 16, v10
	v_pk_fma_f32 v[0:1], v[136:137], v[0:1], v[2:3] op_sel_hi:[0,1,1]
	v_pk_fma_f32 v[2:3], v[138:139], v[0:1], v[66:67] op_sel:[0,1,0] op_sel_hi:[1,0,1]
	v_and_b32_e32 v7, 0xffff0000, v10
	v_pk_fma_f32 v[0:1], v[136:137], v[0:1], v[2:3] op_sel_hi:[0,1,1]
	v_pk_fma_f32 v[2:3], v[148:149], v[0:1], v[14:15]
	v_lshlrev_b32_e32 v14, 16, v12
	v_and_b32_e32 v15, 0xffff0000, v12
	v_pk_fma_f32 v[8:9], v[150:151], v[4:5], v[14:15]
	v_lshlrev_b32_e32 v17, 16, v13
	v_and_b32_e32 v16, 0xffff0000, v13
	v_pk_fma_f32 v[4:5], v[140:141], v[4:5], v[8:9] op_sel:[0,0,1] op_sel_hi:[0,1,0]
	v_pk_fma_f32 v[0:1], v[136:137], v[0:1], v[2:3] op_sel:[0,0,1] op_sel_hi:[0,1,0]
	v_pk_fma_f32 v[8:9], v[142:143], v[4:5], v[16:17] op_sel:[0,1,0] op_sel_hi:[1,0,1]
	v_pk_fma_f32 v[2:3], v[148:149], v[0:1], v[6:7]
	v_lshlrev_b32_e32 v13, 16, v11
	v_and_b32_e32 v12, 0xffff0000, v11
	ds_read2_b32 v[10:11], v194 offset0:96 offset1:164
	ds_read2_b32 v[18:19], v195 offset0:96 offset1:164
	ds_read2_b32 v[20:21], v196 offset0:104 offset1:172
	ds_read2_b32 v[22:23], v197 offset0:104 offset1:172
	ds_read2_b32 v[24:25], v198 offset0:112 offset1:180
	ds_read2_b32 v[26:27], v199 offset0:112 offset1:180
	ds_read2_b32 v[28:29], v200 offset0:120 offset1:188
	ds_read2_b32 v[30:31], v201 offset0:120 offset1:188
	s_waitcnt lgkmcnt(7)
	v_lshlrev_b32_e32 v49, 16, v10
	v_and_b32_e32 v48, 0xffff0000, v10
	v_pk_fma_f32 v[4:5], v[140:141], v[4:5], v[8:9] op_sel_hi:[0,1,1]
	v_pk_fma_f32 v[0:1], v[136:137], v[0:1], v[2:3] op_sel:[0,0,1] op_sel_hi:[0,1,0]
	v_pk_fma_f32 v[8:9], v[142:143], v[4:5], v[48:49] op_sel:[0,1,0] op_sel_hi:[1,0,1]
	v_pk_fma_f32 v[2:3], v[138:139], v[0:1], v[12:13] op_sel:[0,1,0] op_sel_hi:[1,0,1]
	s_waitcnt lgkmcnt(6)
	v_lshlrev_b32_e32 v51, 16, v18
	v_and_b32_e32 v50, 0xffff0000, v18
	v_lshlrev_b32_e32 v53, 16, v11
	v_and_b32_e32 v52, 0xffff0000, v11
	v_pk_fma_f32 v[4:5], v[140:141], v[4:5], v[8:9] op_sel_hi:[0,1,1]
	v_pk_fma_f32 v[0:1], v[136:137], v[0:1], v[2:3] op_sel_hi:[0,1,1]
	v_pk_fma_f32 v[8:9], v[142:143], v[4:5], v[52:53] op_sel:[0,1,0] op_sel_hi:[1,0,1]
	v_pk_fma_f32 v[2:3], v[138:139], v[0:1], v[50:51] op_sel:[0,1,0] op_sel_hi:[1,0,1]
	v_lshlrev_b32_e32 v11, 16, v19
	v_and_b32_e32 v10, 0xffff0000, v19
	s_waitcnt lgkmcnt(5)
	v_lshlrev_b32_e32 v19, 16, v20
	v_and_b32_e32 v18, 0xffff0000, v20
	v_pk_fma_f32 v[4:5], v[140:141], v[4:5], v[8:9] op_sel_hi:[0,1,1]
	v_pk_fma_f32 v[0:1], v[136:137], v[0:1], v[2:3] op_sel_hi:[0,1,1]
	v_pk_fma_f32 v[8:9], v[142:143], v[4:5], v[18:19] op_sel:[0,1,0] op_sel_hi:[1,0,1]
	v_pk_fma_f32 v[2:3], v[138:139], v[0:1], v[10:11] op_sel:[0,1,0] op_sel_hi:[1,0,1]
	s_waitcnt lgkmcnt(4)
	v_lshlrev_b32_e32 v55, 16, v22
	v_and_b32_e32 v54, 0xffff0000, v22
	v_lshlrev_b32_e32 v57, 16, v21
	v_and_b32_e32 v56, 0xffff0000, v21
	v_pk_fma_f32 v[4:5], v[140:141], v[4:5], v[8:9] op_sel_hi:[0,1,1]
	v_pk_fma_f32 v[0:1], v[136:137], v[0:1], v[2:3] op_sel_hi:[0,1,1]
	v_pk_fma_f32 v[8:9], v[142:143], v[4:5], v[56:57] op_sel:[0,1,0] op_sel_hi:[1,0,1]
	v_pk_fma_f32 v[2:3], v[138:139], v[0:1], v[54:55] op_sel:[0,1,0] op_sel_hi:[1,0,1]
	v_lshlrev_b32_e32 v21, 16, v23
	v_and_b32_e32 v20, 0xffff0000, v23
	s_waitcnt lgkmcnt(3)
	v_lshlrev_b32_e32 v23, 16, v24
	v_and_b32_e32 v22, 0xffff0000, v24
	v_pk_fma_f32 v[4:5], v[140:141], v[4:5], v[8:9] op_sel_hi:[0,1,1]
	v_pk_fma_f32 v[0:1], v[136:137], v[0:1], v[2:3] op_sel_hi:[0,1,1]
	v_pk_fma_f32 v[8:9], v[142:143], v[4:5], v[22:23] op_sel:[0,1,0] op_sel_hi:[1,0,1]
	v_pk_fma_f32 v[2:3], v[138:139], v[0:1], v[20:21] op_sel:[0,1,0] op_sel_hi:[1,0,1]
	s_waitcnt lgkmcnt(2)
	v_lshlrev_b32_e32 v59, 16, v26
	v_and_b32_e32 v58, 0xffff0000, v26
	v_lshlrev_b32_e32 v61, 16, v25
	v_and_b32_e32 v60, 0xffff0000, v25
	v_pk_fma_f32 v[4:5], v[140:141], v[4:5], v[8:9] op_sel_hi:[0,1,1]
	v_pk_fma_f32 v[0:1], v[136:137], v[0:1], v[2:3] op_sel_hi:[0,1,1]
	v_pk_fma_f32 v[8:9], v[142:143], v[4:5], v[60:61] op_sel:[0,1,0] op_sel_hi:[1,0,1]
	v_pk_fma_f32 v[2:3], v[138:139], v[0:1], v[58:59] op_sel:[0,1,0] op_sel_hi:[1,0,1]
	v_lshlrev_b32_e32 v25, 16, v27
	v_and_b32_e32 v24, 0xffff0000, v27
	s_waitcnt lgkmcnt(1)
	v_lshlrev_b32_e32 v27, 16, v28
	v_and_b32_e32 v26, 0xffff0000, v28
	v_pk_fma_f32 v[4:5], v[140:141], v[4:5], v[8:9] op_sel_hi:[0,1,1]
	v_pk_fma_f32 v[0:1], v[136:137], v[0:1], v[2:3] op_sel_hi:[0,1,1]
	v_pk_fma_f32 v[8:9], v[142:143], v[4:5], v[26:27] op_sel:[0,1,0] op_sel_hi:[1,0,1]
	v_pk_fma_f32 v[2:3], v[138:139], v[0:1], v[24:25] op_sel:[0,1,0] op_sel_hi:[1,0,1]
	s_waitcnt lgkmcnt(0)
	v_lshlrev_b32_e32 v63, 16, v30
	v_and_b32_e32 v62, 0xffff0000, v30
	v_lshlrev_b32_e32 v65, 16, v29
	v_and_b32_e32 v64, 0xffff0000, v29
	v_pk_fma_f32 v[4:5], v[140:141], v[4:5], v[8:9] op_sel_hi:[0,1,1]
	v_pk_fma_f32 v[0:1], v[136:137], v[0:1], v[2:3] op_sel_hi:[0,1,1]
	v_pk_fma_f32 v[8:9], v[142:143], v[4:5], v[64:65] op_sel:[0,1,0] op_sel_hi:[1,0,1]
	v_pk_fma_f32 v[2:3], v[138:139], v[0:1], v[62:63] op_sel:[0,1,0] op_sel_hi:[1,0,1]
	v_pk_fma_f32 v[4:5], v[140:141], v[4:5], v[8:9] op_sel_hi:[0,1,1]
	v_lshlrev_b32_e32 v9, 16, v31
	v_and_b32_e32 v8, 0xffff0000, v31
	v_pk_fma_f32 v[0:1], v[136:137], v[0:1], v[2:3] op_sel_hi:[0,1,1]
	v_pk_fma_f32 v[2:3], v[138:139], v[0:1], v[8:9] op_sel:[0,1,0] op_sel_hi:[1,0,1]
	s_waitcnt lgkmcnt(0)
	s_nop 0
	v_pk_fma_f32 v[0:1], v[136:137], v[0:1], v[2:3] op_sel_hi:[0,1,1]
	v_pk_mov_b32 v[2:3], v[4:5], v[4:5] op_sel:[1,0]
	v_lshl_add_u64 v[4:5], v[90:91], 0, s[20:21]
	s_add_u32 s20, s10, s12
	s_addc_u32 s21, s11, 0
	s_lshl_b64 s[20:21], s[20:21], 9
	global_store_dwordx2 v[4:5], v[2:3], off
	v_pk_mov_b32 v[0:1], v[0:1], v[0:1] op_sel:[1,0]
	v_lshl_add_u64 v[2:3], v[90:91], 0, s[20:21]
	global_store_dwordx2 v[2:3], v[0:1], off
	global_load_dwordx4 v[76:79], v[112:113], off
	global_load_dwordx4 v[72:75], v[114:115], off
	global_load_dwordx4 v[68:71], v[116:117], off
	global_load_dwordx4 v[64:67], v[118:119], off
	global_load_dwordx4 v[60:63], v[120:121], off
	global_load_dwordx4 v[56:59], v[122:123], off
	global_load_dwordx4 v[52:55], v[126:127], off
	global_load_dwordx4 v[48:51], v[128:129], off
	global_load_dwordx2 v[84:85], v[130:131], off
	global_load_dwordx2 v[80:81], v[132:133], off
	s_waitcnt vmcnt(9)
	v_mfma_f32_32x32x16_bf16 v[0:15], v[76:79], v[44:47], 0
	s_add_u32 s20, s10, s13
	s_addc_u32 s21, s11, 0
	s_lshl_b64 s[20:21], s[20:21], 9
	s_add_u32 s10, s10, s14
	s_addc_u32 s11, s11, 0
	s_lshl_b64 s[10:11], s[10:11], 9
	s_add_i32 s8, s8, s82
	s_waitcnt vmcnt(8)
	v_mfma_f32_32x32x16_bf16 v[16:31], v[72:75], v[40:43], 0
	s_nop 2
	v_cvt_pk_bf16_f32 v0, v0, v1
	v_cvt_pk_bf16_f32 v1, v2, v3
	v_cvt_pk_bf16_f32 v4, v4, v5
	v_cvt_pk_bf16_f32 v5, v6, v7
	ds_write2_b64 v125, v[0:1], v[4:5] offset1:2
	v_cvt_pk_bf16_f32 v4, v12, v13
	v_cvt_pk_bf16_f32 v5, v14, v15
	s_nop 1
	v_cvt_pk_bf16_f32 v2, v16, v17
	v_cvt_pk_bf16_f32 v3, v18, v19
	v_cvt_pk_bf16_f32 v0, v20, v21
	v_cvt_pk_bf16_f32 v1, v22, v23
	ds_write2_b64 v192, v[2:3], v[0:1] offset0:64 offset1:66
	v_cvt_pk_bf16_f32 v0, v8, v9
	v_cvt_pk_bf16_f32 v1, v10, v11
	v_cvt_pk_bf16_f32 v2, v24, v25
	v_cvt_pk_bf16_f32 v3, v26, v27
	ds_write2_b64 v125, v[0:1], v[4:5] offset0:4 offset1:6
	v_cvt_pk_bf16_f32 v0, v28, v29
	v_cvt_pk_bf16_f32 v1, v30, v31
	ds_write2_b64 v192, v[2:3], v[0:1] offset0:68 offset1:70
	s_waitcnt vmcnt(7)
	v_mfma_f32_32x32x16_bf16 v[0:15], v[68:71], v[44:47], 0
	s_waitcnt vmcnt(1)
	v_xor_b32_e32 v87, 0x80000000, v85
	v_mov_b32_e32 v86, v85
	s_waitcnt vmcnt(0)
	v_xor_b32_e32 v83, 0x80000000, v81
	v_mov_b32_e32 v82, v81
	s_add_i32 s15, s15, s16
	s_cmpk_gt_i32 s8, 0x1ff
	s_cselect_b32 s100, 0x1ff, s8
	s_mul_i32 s100, s100, 64
	v_or_b32_e32 v250, s100, v124
	v_mul_u32_u24_e32 v250, 0x2400, v250
	v_mov_b32_e32 v251, 0
	v_lshl_add_u64 v[250:251], v[250:251], 0, v[134:135]
	v_lshl_add_u64 v[250:251], v[250:251], 0, s[0:1]
	v_lshl_add_u64 v[250:251], v[250:251], 0, v[88:89]
	v_lshl_add_u64 v[252:253], v[250:251], 0, s[4:5]
	v_lshl_add_u64 v[254:255], v[250:251], 0, s[6:7]
	global_load_dwordx4 v[218:221], v[252:253], off
	global_load_dwordx4 v[226:229], v[252:253], off offset:256
	global_load_dwordx4 v[222:225], v[254:255], off
	global_load_dwordx4 v[230:233], v[254:255], off offset:256
	s_nop 3
	v_cvt_pk_bf16_f32 v0, v0, v1
	v_mfma_f32_32x32x16_bf16 v[16:31], v[64:67], v[40:43], 0
	v_cvt_pk_bf16_f32 v1, v2, v3
	v_cvt_pk_bf16_f32 v4, v4, v5
	v_cvt_pk_bf16_f32 v5, v6, v7
	ds_write2_b64 v125, v[0:1], v[4:5] offset0:8 offset1:10
	v_cvt_pk_bf16_f32 v4, v12, v13
	v_cvt_pk_bf16_f32 v5, v14, v15
	s_nop 5
	v_cvt_pk_bf16_f32 v2, v16, v17
	v_cvt_pk_bf16_f32 v3, v18, v19
	v_cvt_pk_bf16_f32 v0, v20, v21
	v_cvt_pk_bf16_f32 v1, v22, v23
	ds_write2_b64 v192, v[2:3], v[0:1] offset0:72 offset1:74
	v_cvt_pk_bf16_f32 v0, v8, v9
	v_cvt_pk_bf16_f32 v1, v10, v11
	v_cvt_pk_bf16_f32 v2, v24, v25
	v_cvt_pk_bf16_f32 v3, v26, v27
	ds_write2_b64 v125, v[0:1], v[4:5] offset0:12 offset1:14
	v_cvt_pk_bf16_f32 v0, v28, v29
	v_cvt_pk_bf16_f32 v1, v30, v31
	ds_write2_b64 v192, v[2:3], v[0:1] offset0:76 offset1:78
	v_mfma_f32_32x32x16_bf16 v[0:15], v[60:63], v[44:47], 0
	v_mfma_f32_32x32x16_bf16 v[16:31], v[56:59], v[40:43], 0
	s_nop 10
	v_cvt_pk_bf16_f32 v0, v0, v1
	v_cvt_pk_bf16_f32 v1, v2, v3
	v_cvt_pk_bf16_f32 v4, v4, v5
	v_cvt_pk_bf16_f32 v5, v6, v7
	ds_write2_b64 v125, v[0:1], v[4:5] offset0:16 offset1:18
	v_cvt_pk_bf16_f32 v4, v12, v13
	v_cvt_pk_bf16_f32 v5, v14, v15
	v_cvt_pk_bf16_f32 v2, v16, v17
	v_cvt_pk_bf16_f32 v3, v18, v19
	v_cvt_pk_bf16_f32 v0, v20, v21
	v_cvt_pk_bf16_f32 v1, v22, v23
	ds_write2_b64 v192, v[2:3], v[0:1] offset0:80 offset1:82
	v_cvt_pk_bf16_f32 v0, v8, v9
	v_cvt_pk_bf16_f32 v1, v10, v11
	v_cvt_pk_bf16_f32 v2, v24, v25
	v_cvt_pk_bf16_f32 v3, v26, v27
	ds_write2_b64 v125, v[0:1], v[4:5] offset0:20 offset1:22
	v_cvt_pk_bf16_f32 v0, v28, v29
	v_cvt_pk_bf16_f32 v1, v30, v31
	ds_write2_b64 v192, v[2:3], v[0:1] offset0:84 offset1:86
	v_mfma_f32_32x32x16_bf16 v[0:15], v[52:55], v[44:47], 0
	v_mfma_f32_32x32x16_bf16 v[16:31], v[48:51], v[40:43], 0
	s_nop 10
	v_cvt_pk_bf16_f32 v0, v0, v1
	v_cvt_pk_bf16_f32 v1, v2, v3
	v_cvt_pk_bf16_f32 v4, v4, v5
	v_cvt_pk_bf16_f32 v5, v6, v7
	ds_write2_b64 v125, v[0:1], v[4:5] offset0:24 offset1:26
	v_cvt_pk_bf16_f32 v4, v12, v13
	v_cvt_pk_bf16_f32 v5, v14, v15
	v_cvt_pk_bf16_f32 v2, v16, v17
	v_cvt_pk_bf16_f32 v3, v18, v19
	v_cvt_pk_bf16_f32 v0, v20, v21
	v_cvt_pk_bf16_f32 v1, v22, v23
	ds_write2_b64 v192, v[2:3], v[0:1] offset0:88 offset1:90
	v_cvt_pk_bf16_f32 v0, v8, v9
	v_cvt_pk_bf16_f32 v1, v10, v11
	v_cvt_pk_bf16_f32 v2, v24, v25
	v_cvt_pk_bf16_f32 v3, v26, v27
	ds_write2_b64 v125, v[0:1], v[4:5] offset0:28 offset1:30
	v_cvt_pk_bf16_f32 v0, v28, v29
	v_cvt_pk_bf16_f32 v1, v30, v31
	ds_write2_b64 v192, v[2:3], v[0:1] offset0:92 offset1:94
	s_waitcnt lgkmcnt(0)
	ds_read2_b32 v[0:1], v145 offset1:68
	ds_read2_b32 v[2:3], v215 offset0:128 offset1:196
	ds_read2_b32 v[4:5], v145 offset0:136 offset1:204
	ds_read2_b32 v[6:7], v216 offset0:8 offset1:76
	ds_read2_b32 v[8:9], v217 offset0:16 offset1:84
	ds_read2_b32 v[10:11], v216 offset0:144 offset1:212
	ds_read2_b32 v[12:13], v217 offset0:152 offset1:220
	ds_read2_b32 v[14:15], v210 offset0:24 offset1:92
	s_waitcnt lgkmcnt(7)
	v_lshlrev_b32_e32 v17, 16, v0
	v_and_b32_e32 v16, 0xffff0000, v0
	v_pk_fma_f32 v[16:17], v[86:87], 0, v[16:17] op_sel_hi:[1,0,1]
	v_lshlrev_b32_e32 v21, 16, v1
	v_and_b32_e32 v20, 0xffff0000, v1
	v_pk_fma_f32 v[16:17], v[84:85], 0, v[16:17] op_sel_hi:[0,0,1]
	v_pk_fma_f32 v[20:21], v[86:87], v[16:17], v[20:21] op_sel:[0,1,0] op_sel_hi:[1,0,1]
	s_waitcnt lgkmcnt(6)
	v_lshlrev_b32_e32 v19, 16, v2
	v_and_b32_e32 v18, 0xffff0000, v2
	v_lshlrev_b32_e32 v1, 16, v3
	v_and_b32_e32 v0, 0xffff0000, v3
	s_waitcnt lgkmcnt(5)
	v_lshlrev_b32_e32 v3, 16, v4
	v_and_b32_e32 v2, 0xffff0000, v4
	v_pk_fma_f32 v[16:17], v[84:85], v[16:17], v[20:21] op_sel_hi:[0,1,1]
	v_pk_fma_f32 v[2:3], v[86:87], v[16:17], v[2:3] op_sel:[0,1,0] op_sel_hi:[1,0,1]
	s_waitcnt lgkmcnt(4)
	v_lshlrev_b32_e32 v23, 16, v6
	v_pk_fma_f32 v[2:3], v[84:85], v[16:17], v[2:3] op_sel_hi:[0,1,1]
	v_pk_fma_f32 v[16:17], v[82:83], 0, v[18:19] op_sel_hi:[1,0,1]
	v_and_b32_e32 v22, 0xffff0000, v6
	v_pk_fma_f32 v[16:17], v[80:81], 0, v[16:17] op_sel_hi:[0,0,1]
	v_pk_fma_f32 v[0:1], v[82:83], v[16:17], v[0:1] op_sel:[0,1,0] op_sel_hi:[1,0,1]
	v_lshlrev_b32_e32 v4, 16, v5
	v_and_b32_e32 v5, 0xffff0000, v5
	v_mov_b32_e32 v42, v87
	v_mov_b32_e32 v43, v85
	v_pk_fma_f32 v[0:1], v[80:81], v[16:17], v[0:1] op_sel_hi:[0,1,1]
	v_pk_fma_f32 v[4:5], v[42:43], v[2:3], v[4:5]
	v_pk_fma_f32 v[16:17], v[82:83], v[0:1], v[22:23] op_sel:[0,1,0] op_sel_hi:[1,0,1]
	v_pk_fma_f32 v[2:3], v[84:85], v[2:3], v[4:5] op_sel:[0,0,1] op_sel_hi:[0,1,0]
	v_pk_fma_f32 v[0:1], v[80:81], v[0:1], v[16:17] op_sel_hi:[0,1,1]
	s_waitcnt lgkmcnt(3)
	v_lshlrev_b32_e32 v16, 16, v8
	v_and_b32_e32 v17, 0xffff0000, v8
	v_pk_fma_f32 v[4:5], v[42:43], v[2:3], v[16:17]
	v_lshlrev_b32_e32 v21, 16, v9
	v_and_b32_e32 v20, 0xffff0000, v9
	v_pk_fma_f32 v[2:3], v[84:85], v[2:3], v[4:5] op_sel:[0,0,1] op_sel_hi:[0,1,0]
	v_pk_fma_f32 v[4:5], v[86:87], v[2:3], v[20:21] op_sel:[0,1,0] op_sel_hi:[1,0,1]
	s_waitcnt lgkmcnt(2)
	v_lshlrev_b32_e32 v18, 16, v10
	v_and_b32_e32 v19, 0xffff0000, v10
	v_lshlrev_b32_e32 v9, 16, v11
	v_and_b32_e32 v8, 0xffff0000, v11
	s_waitcnt lgkmcnt(1)
	v_lshlrev_b32_e32 v11, 16, v12
	v_and_b32_e32 v10, 0xffff0000, v12
	v_pk_fma_f32 v[2:3], v[84:85], v[2:3], v[4:5] op_sel_hi:[0,1,1]
	v_pk_fma_f32 v[4:5], v[86:87], v[2:3], v[10:11] op_sel:[0,1,0] op_sel_hi:[1,0,1]
	v_lshlrev_b32_e32 v25, 16, v13
	v_and_b32_e32 v24, 0xffff0000, v13
	v_pk_fma_f32 v[2:3], v[84:85], v[2:3], v[4:5] op_sel_hi:[0,1,1]
	v_lshlrev_b32_e32 v6, 16, v7
	v_and_b32_e32 v7, 0xffff0000, v7
	v_mov_b32_e32 v40, v83
	v_mov_b32_e32 v41, v81
	v_pk_fma_f32 v[4:5], v[86:87], v[2:3], v[24:25] op_sel:[0,1,0] op_sel_hi:[1,0,1]
	v_pk_fma_f32 v[6:7], v[40:41], v[0:1], v[6:7]
	s_waitcnt lgkmcnt(0)
	v_lshlrev_b32_e32 v23, 16, v14
	v_and_b32_e32 v22, 0xffff0000, v14
	v_lshlrev_b32_e32 v13, 16, v15
	v_and_b32_e32 v12, 0xffff0000, v15
	ds_read2_b32 v[14:15], v211 offset0:32 offset1:100
	ds_read2_b32 v[26:27], v210 offset0:160 offset1:228
	ds_read2_b32 v[28:29], v211 offset0:168 offset1:236
	ds_read2_b32 v[30:31], v212 offset0:40 offset1:108
	ds_read2_b32 v[44:45], v213 offset0:48 offset1:116
	ds_read2_b32 v[46:47], v212 offset0:176 offset1:244
	ds_read2_b32 v[136:137], v213 offset0:184 offset1:252
	ds_read2_b32 v[138:139], v214 offset0:56 offset1:124
	s_waitcnt lgkmcnt(7)
	v_lshlrev_b32_e32 v141, 16, v14
	v_and_b32_e32 v140, 0xffff0000, v14
	v_pk_fma_f32 v[2:3], v[84:85], v[2:3], v[4:5] op_sel_hi:[0,1,1]
	v_pk_fma_f32 v[4:5], v[86:87], v[2:3], v[140:141] op_sel:[0,1,0] op_sel_hi:[1,0,1]
	v_pk_fma_f32 v[0:1], v[80:81], v[0:1], v[6:7] op_sel:[0,0,1] op_sel_hi:[0,1,0]
	v_lshlrev_b32_e32 v149, 16, v15
	v_and_b32_e32 v148, 0xffff0000, v15
	v_pk_fma_f32 v[2:3], v[84:85], v[2:3], v[4:5] op_sel_hi:[0,1,1]
	v_pk_fma_f32 v[6:7], v[40:41], v[0:1], v[18:19]
	v_pk_fma_f32 v[4:5], v[86:87], v[2:3], v[148:149] op_sel:[0,1,0] op_sel_hi:[1,0,1]
	v_pk_fma_f32 v[0:1], v[80:81], v[0:1], v[6:7] op_sel:[0,0,1] op_sel_hi:[0,1,0]
	s_waitcnt lgkmcnt(6)
	v_lshlrev_b32_e32 v143, 16, v26
	v_and_b32_e32 v142, 0xffff0000, v26
	v_lshlrev_b32_e32 v15, 16, v27
	v_and_b32_e32 v14, 0xffff0000, v27
	s_waitcnt lgkmcnt(5)
	v_lshlrev_b32_e32 v27, 16, v28
	v_and_b32_e32 v26, 0xffff0000, v28
	v_pk_fma_f32 v[2:3], v[84:85], v[2:3], v[4:5] op_sel_hi:[0,1,1]
	v_pk_fma_f32 v[6:7], v[82:83], v[0:1], v[8:9] op_sel:[0,1,0] op_sel_hi:[1,0,1]
	v_pk_fma_f32 v[4:5], v[86:87], v[2:3], v[26:27] op_sel:[0,1,0] op_sel_hi:[1,0,1]
	v_pk_fma_f32 v[0:1], v[80:81], v[0:1], v[6:7] op_sel_hi:[0,1,1]
	v_lshlrev_b32_e32 v153, 16, v29
	v_and_b32_e32 v152, 0xffff0000, v29
	v_pk_fma_f32 v[2:3], v[84:85], v[2:3], v[4:5] op_sel_hi:[0,1,1]
	v_pk_fma_f32 v[6:7], v[82:83], v[0:1], v[22:23] op_sel:[0,1,0] op_sel_hi:[1,0,1]
	v_pk_fma_f32 v[4:5], v[86:87], v[2:3], v[152:153] op_sel:[0,1,0] op_sel_hi:[1,0,1]
	v_pk_fma_f32 v[0:1], v[80:81], v[0:1], v[6:7] op_sel_hi:[0,1,1]
	s_waitcnt lgkmcnt(4)
	v_lshlrev_b32_e32 v151, 16, v30
	v_and_b32_e32 v150, 0xffff0000, v30
	v_lshlrev_b32_e32 v29, 16, v31
	v_and_b32_e32 v28, 0xffff0000, v31
	s_waitcnt lgkmcnt(3)
	v_lshlrev_b32_e32 v31, 16, v44
	v_and_b32_e32 v30, 0xffff0000, v44
	v_pk_fma_f32 v[2:3], v[84:85], v[2:3], v[4:5] op_sel_hi:[0,1,1]
	v_pk_fma_f32 v[6:7], v[82:83], v[0:1], v[12:13] op_sel:[0,1,0] op_sel_hi:[1,0,1]
	v_pk_fma_f32 v[4:5], v[86:87], v[2:3], v[30:31] op_sel:[0,1,0] op_sel_hi:[1,0,1]
	v_pk_fma_f32 v[0:1], v[80:81], v[0:1], v[6:7] op_sel_hi:[0,1,1]
	v_lshlrev_b32_e32 v44, 16, v45
	v_and_b32_e32 v45, 0xffff0000, v45
	v_pk_fma_f32 v[2:3], v[84:85], v[2:3], v[4:5] op_sel_hi:[0,1,1]
	v_pk_fma_f32 v[6:7], v[82:83], v[0:1], v[142:143] op_sel:[0,1,0] op_sel_hi:[1,0,1]
	v_pk_fma_f32 v[4:5], v[42:43], v[2:3], v[44:45]
	v_pk_fma_f32 v[0:1], v[80:81], v[0:1], v[6:7] op_sel_hi:[0,1,1]
	v_pk_fma_f32 v[6:7], v[82:83], v[0:1], v[14:15] op_sel:[0,1,0] op_sel_hi:[1,0,1]
	s_waitcnt lgkmcnt(1)
	v_lshlrev_b32_e32 v8, 16, v136
	v_and_b32_e32 v9, 0xffff0000, v136
	v_pk_fma_f32 v[2:3], v[84:85], v[2:3], v[4:5] op_sel:[0,0,1] op_sel_hi:[0,1,0]
	v_pk_fma_f32 v[0:1], v[80:81], v[0:1], v[6:7] op_sel_hi:[0,1,1]
	v_pk_fma_f32 v[4:5], v[42:43], v[2:3], v[8:9]
	v_pk_fma_f32 v[6:7], v[82:83], v[0:1], v[150:151] op_sel:[0,1,0] op_sel_hi:[1,0,1]
	v_lshlrev_b32_e32 v13, 16, v137
	v_and_b32_e32 v12, 0xffff0000, v137
	v_pk_fma_f32 v[2:3], v[84:85], v[2:3], v[4:5] op_sel:[0,0,1] op_sel_hi:[0,1,0]
	v_pk_fma_f32 v[0:1], v[80:81], v[0:1], v[6:7] op_sel_hi:[0,1,1]
	v_pk_fma_f32 v[4:5], v[86:87], v[2:3], v[12:13] op_sel:[0,1,0] op_sel_hi:[1,0,1]
	v_pk_fma_f32 v[6:7], v[82:83], v[0:1], v[28:29] op_sel:[0,1,0] op_sel_hi:[1,0,1]
	ds_read2_b32 v[16:17], v202 offset0:64 offset1:132
	ds_read2_b32 v[18:19], v203 offset0:64 offset1:132
	ds_read2_b32 v[20:21], v204 offset0:72 offset1:140
	ds_read2_b32 v[22:23], v205 offset0:72 offset1:140
	ds_read2_b32 v[24:25], v206 offset0:80 offset1:148
	ds_read2_b32 v[26:27], v207 offset0:80 offset1:148
	ds_read2_b32 v[28:29], v208 offset0:88 offset1:156
	ds_read2_b32 v[30:31], v209 offset0:88 offset1:156
	s_waitcnt lgkmcnt(7)
	v_lshlrev_b32_e32 v45, 16, v16
	v_and_b32_e32 v44, 0xffff0000, v16
	v_pk_fma_f32 v[2:3], v[84:85], v[2:3], v[4:5] op_sel_hi:[0,1,1]
	v_pk_fma_f32 v[4:5], v[86:87], v[2:3], v[44:45] op_sel:[0,1,0] op_sel_hi:[1,0,1]
	v_lshlrev_b32_e32 v137, 16, v17
	v_and_b32_e32 v136, 0xffff0000, v17
	v_pk_fma_f32 v[2:3], v[84:85], v[2:3], v[4:5] op_sel_hi:[0,1,1]
	v_pk_fma_f32 v[4:5], v[86:87], v[2:3], v[136:137] op_sel:[0,1,0] op_sel_hi:[1,0,1]
	v_lshlrev_b32_e32 v155, 16, v46
	v_and_b32_e32 v154, 0xffff0000, v46
	v_lshlrev_b32_e32 v10, 16, v47
	v_and_b32_e32 v11, 0xffff0000, v47
	s_waitcnt lgkmcnt(6)
	v_lshlrev_b32_e32 v47, 16, v18
	v_and_b32_e32 v46, 0xffff0000, v18
	v_lshlrev_b32_e32 v17, 16, v19
	v_and_b32_e32 v16, 0xffff0000, v19
	s_waitcnt lgkmcnt(5)
	v_lshlrev_b32_e32 v19, 16, v20
	v_and_b32_e32 v18, 0xffff0000, v20
	v_pk_fma_f32 v[2:3], v[84:85], v[2:3], v[4:5] op_sel_hi:[0,1,1]
	v_pk_fma_f32 v[0:1], v[80:81], v[0:1], v[6:7] op_sel_hi:[0,1,1]
	v_pk_fma_f32 v[4:5], v[86:87], v[2:3], v[18:19] op_sel:[0,1,0] op_sel_hi:[1,0,1]
	v_pk_fma_f32 v[6:7], v[82:83], v[0:1], v[154:155] op_sel:[0,1,0] op_sel_hi:[1,0,1]
	v_lshlrev_b32_e32 v141, 16, v21
	v_and_b32_e32 v140, 0xffff0000, v21
	v_pk_fma_f32 v[2:3], v[84:85], v[2:3], v[4:5] op_sel_hi:[0,1,1]
	v_pk_fma_f32 v[0:1], v[80:81], v[0:1], v[6:7] op_sel_hi:[0,1,1]
	v_pk_fma_f32 v[4:5], v[86:87], v[2:3], v[140:141] op_sel:[0,1,0] op_sel_hi:[1,0,1]
	v_pk_fma_f32 v[6:7], v[40:41], v[0:1], v[10:11]
	v_lshlrev_b32_e32 v10, 16, v138
	v_and_b32_e32 v11, 0xffff0000, v138
	v_lshlrev_b32_e32 v15, 16, v139
	v_and_b32_e32 v14, 0xffff0000, v139
	s_waitcnt lgkmcnt(4)
	v_lshlrev_b32_e32 v139, 16, v22
	v_and_b32_e32 v138, 0xffff0000, v22
	v_lshlrev_b32_e32 v21, 16, v23
	v_and_b32_e32 v20, 0xffff0000, v23
	s_waitcnt lgkmcnt(3)
	v_lshlrev_b32_e32 v23, 16, v24
	v_and_b32_e32 v22, 0xffff0000, v24
	v_pk_fma_f32 v[2:3], v[84:85], v[2:3], v[4:5] op_sel_hi:[0,1,1]
	v_pk_fma_f32 v[4:5], v[86:87], v[2:3], v[22:23] op_sel:[0,1,0] op_sel_hi:[1,0,1]
	v_lshlrev_b32_e32 v149, 16, v25
	v_and_b32_e32 v148, 0xffff0000, v25
	v_pk_fma_f32 v[2:3], v[84:85], v[2:3], v[4:5] op_sel_hi:[0,1,1]
	v_pk_fma_f32 v[4:5], v[86:87], v[2:3], v[148:149] op_sel:[0,1,0] op_sel_hi:[1,0,1]
	s_waitcnt lgkmcnt(2)
	v_lshlrev_b32_e32 v143, 16, v26
	v_and_b32_e32 v142, 0xffff0000, v26
	v_lshlrev_b32_e32 v25, 16, v27
	v_and_b32_e32 v24, 0xffff0000, v27
	s_waitcnt lgkmcnt(1)
	v_lshlrev_b32_e32 v27, 16, v28
	v_and_b32_e32 v26, 0xffff0000, v28
	v_pk_fma_f32 v[2:3], v[84:85], v[2:3], v[4:5] op_sel_hi:[0,1,1]
	v_pk_fma_f32 v[4:5], v[86:87], v[2:3], v[26:27] op_sel:[0,1,0] op_sel_hi:[1,0,1]
	v_pk_fma_f32 v[0:1], v[80:81], v[0:1], v[6:7] op_sel:[0,0,1] op_sel_hi:[0,1,0]
	v_pk_fma_f32 v[44:45], v[84:85], v[2:3], v[4:5] op_sel_hi:[0,1,1]
	v_pk_fma_f32 v[4:5], v[40:41], v[0:1], v[10:11]
	s_waitcnt lgkmcnt(0)
	v_lshlrev_b32_e32 v151, 16, v30
	v_pk_fma_f32 v[0:1], v[80:81], v[0:1], v[4:5] op_sel:[0,0,1] op_sel_hi:[0,1,0]
	v_pk_fma_f32 v[4:5], v[82:83], v[0:1], v[14:15] op_sel:[0,1,0] op_sel_hi:[1,0,1]
	v_and_b32_e32 v150, 0xffff0000, v30
	v_pk_fma_f32 v[0:1], v[80:81], v[0:1], v[4:5] op_sel_hi:[0,1,1]
	v_pk_fma_f32 v[4:5], v[82:83], v[0:1], v[46:47] op_sel:[0,1,0] op_sel_hi:[1,0,1]
	v_lshlrev_b32_e32 v2, 16, v31
	v_pk_fma_f32 v[0:1], v[80:81], v[0:1], v[4:5] op_sel_hi:[0,1,1]
	v_pk_fma_f32 v[4:5], v[82:83], v[0:1], v[16:17] op_sel:[0,1,0] op_sel_hi:[1,0,1]
	v_and_b32_e32 v3, 0xffff0000, v31
	v_pk_fma_f32 v[0:1], v[80:81], v[0:1], v[4:5] op_sel_hi:[0,1,1]
	v_pk_fma_f32 v[4:5], v[82:83], v[0:1], v[138:139] op_sel:[0,1,0] op_sel_hi:[1,0,1]
	v_lshlrev_b32_e32 v28, 16, v29
	v_pk_fma_f32 v[0:1], v[80:81], v[0:1], v[4:5] op_sel_hi:[0,1,1]
	v_pk_fma_f32 v[4:5], v[82:83], v[0:1], v[20:21] op_sel:[0,1,0] op_sel_hi:[1,0,1]
	v_and_b32_e32 v29, 0xffff0000, v29
	v_pk_fma_f32 v[0:1], v[80:81], v[0:1], v[4:5] op_sel_hi:[0,1,1]
	v_pk_fma_f32 v[4:5], v[82:83], v[0:1], v[142:143] op_sel:[0,1,0] op_sel_hi:[1,0,1]
	v_pk_fma_f32 v[136:137], v[42:43], v[44:45], v[28:29]
	v_pk_fma_f32 v[0:1], v[80:81], v[0:1], v[4:5] op_sel_hi:[0,1,1]
	v_pk_fma_f32 v[4:5], v[82:83], v[0:1], v[24:25] op_sel:[0,1,0] op_sel_hi:[1,0,1]
	v_mfma_f32_32x32x16_bf16 v[16:31], v[72:75], v[32:35], 0
	v_fma_f32 v0, v80, v0, v4
	v_fma_f32 v1, v80, v1, v5
	v_fma_f32 v4, v82, v1, v150
	v_fma_f32 v5, v83, v0, v151
	v_fma_f32 v46, v80, v0, v4
	v_fma_f32 v47, v80, v1, v5
	v_pk_fma_f32 v[138:139], v[40:41], v[46:47], v[2:3]
	ds_read2_b32 v[0:1], v194 offset0:96 offset1:164
	ds_read2_b32 v[2:3], v195 offset0:96 offset1:164
	ds_read2_b32 v[4:5], v196 offset0:104 offset1:172
	ds_read2_b32 v[6:7], v197 offset0:104 offset1:172
	ds_read2_b32 v[8:9], v198 offset0:112 offset1:180
	ds_read2_b32 v[10:11], v199 offset0:112 offset1:180
	ds_read2_b32 v[12:13], v200 offset0:120 offset1:188
	ds_read2_b32 v[14:15], v201 offset0:120 offset1:188
	s_waitcnt lgkmcnt(7)
	v_lshlrev_b32_e32 v160, 16, v0
	v_and_b32_e32 v161, 0xffff0000, v0
	s_waitcnt lgkmcnt(6)
	v_lshlrev_b32_e32 v140, 16, v2
	v_and_b32_e32 v141, 0xffff0000, v2
	v_lshlrev_b32_e32 v163, 16, v1
	v_and_b32_e32 v162, 0xffff0000, v1
	v_lshlrev_b32_e32 v143, 16, v3
	v_and_b32_e32 v142, 0xffff0000, v3
	s_waitcnt lgkmcnt(5)
	v_lshlrev_b32_e32 v165, 16, v4
	v_and_b32_e32 v164, 0xffff0000, v4
	s_waitcnt lgkmcnt(4)
	v_lshlrev_b32_e32 v149, 16, v6
	v_and_b32_e32 v148, 0xffff0000, v6
	v_lshlrev_b32_e32 v167, 16, v5
	v_and_b32_e32 v166, 0xffff0000, v5
	v_lshlrev_b32_e32 v151, 16, v7
	v_and_b32_e32 v150, 0xffff0000, v7
	s_waitcnt lgkmcnt(3)
	v_lshlrev_b32_e32 v169, 16, v8
	v_and_b32_e32 v168, 0xffff0000, v8
	s_waitcnt lgkmcnt(2)
	v_lshlrev_b32_e32 v153, 16, v10
	v_and_b32_e32 v152, 0xffff0000, v10
	v_lshlrev_b32_e32 v171, 16, v9
	v_and_b32_e32 v170, 0xffff0000, v9
	v_lshlrev_b32_e32 v155, 16, v11
	v_and_b32_e32 v154, 0xffff0000, v11
	s_waitcnt lgkmcnt(1)
	v_lshlrev_b32_e32 v173, 16, v12
	v_and_b32_e32 v172, 0xffff0000, v12
	s_waitcnt lgkmcnt(0)
	v_lshlrev_b32_e32 v157, 16, v14
	v_and_b32_e32 v156, 0xffff0000, v14
	v_lshlrev_b32_e32 v175, 16, v13
	v_and_b32_e32 v174, 0xffff0000, v13
	v_lshlrev_b32_e32 v159, 16, v15
	v_and_b32_e32 v158, 0xffff0000, v15
	v_mfma_f32_32x32x16_bf16 v[0:15], v[76:79], v[36:39], 0
	s_waitcnt lgkmcnt(0)
	s_nop 11
	v_cvt_pk_bf16_f32 v0, v0, v1
	v_cvt_pk_bf16_f32 v1, v2, v3
	v_cvt_pk_bf16_f32 v4, v4, v5
	v_cvt_pk_bf16_f32 v5, v6, v7
	v_cvt_pk_bf16_f32 v2, v16, v17
	v_cvt_pk_bf16_f32 v3, v18, v19
	ds_write2_b64 v125, v[0:1], v[4:5] offset1:2
	v_cvt_pk_bf16_f32 v0, v20, v21
	v_cvt_pk_bf16_f32 v1, v22, v23
	ds_write2_b64 v192, v[2:3], v[0:1] offset0:64 offset1:66
	v_cvt_pk_bf16_f32 v0, v8, v9
	v_cvt_pk_bf16_f32 v1, v10, v11
	v_cvt_pk_bf16_f32 v4, v12, v13
	v_cvt_pk_bf16_f32 v5, v14, v15
	v_cvt_pk_bf16_f32 v2, v24, v25
	v_cvt_pk_bf16_f32 v3, v26, v27
	ds_write2_b64 v125, v[0:1], v[4:5] offset0:4 offset1:6
	v_cvt_pk_bf16_f32 v0, v28, v29
	v_cvt_pk_bf16_f32 v1, v30, v31
	ds_write2_b64 v192, v[2:3], v[0:1] offset0:68 offset1:70
	v_mfma_f32_32x32x16_bf16 v[0:15], v[68:71], v[36:39], 0
	v_mfma_f32_32x32x16_bf16 v[16:31], v[64:67], v[32:35], 0
	s_nop 10
	v_cvt_pk_bf16_f32 v0, v0, v1
	v_cvt_pk_bf16_f32 v1, v2, v3
	v_cvt_pk_bf16_f32 v4, v4, v5
	v_cvt_pk_bf16_f32 v5, v6, v7
	ds_write2_b64 v125, v[0:1], v[4:5] offset0:8 offset1:10
	v_cvt_pk_bf16_f32 v4, v12, v13
	v_cvt_pk_bf16_f32 v5, v14, v15
	v_cvt_pk_bf16_f32 v2, v16, v17
	v_cvt_pk_bf16_f32 v3, v18, v19
	v_cvt_pk_bf16_f32 v0, v20, v21
	v_cvt_pk_bf16_f32 v1, v22, v23
	ds_write2_b64 v192, v[2:3], v[0:1] offset0:72 offset1:74
	v_cvt_pk_bf16_f32 v0, v8, v9
	v_cvt_pk_bf16_f32 v1, v10, v11
	v_cvt_pk_bf16_f32 v2, v24, v25
	v_cvt_pk_bf16_f32 v3, v26, v27
	ds_write2_b64 v125, v[0:1], v[4:5] offset0:12 offset1:14
	v_cvt_pk_bf16_f32 v0, v28, v29
	v_cvt_pk_bf16_f32 v1, v30, v31
	ds_write2_b64 v192, v[2:3], v[0:1] offset0:76 offset1:78
	v_mfma_f32_32x32x16_bf16 v[0:15], v[60:63], v[36:39], 0
	v_mfma_f32_32x32x16_bf16 v[16:31], v[56:59], v[32:35], 0
	s_nop 10
	v_cvt_pk_bf16_f32 v0, v0, v1
	v_cvt_pk_bf16_f32 v1, v2, v3
	v_cvt_pk_bf16_f32 v4, v4, v5
	v_cvt_pk_bf16_f32 v5, v6, v7
	ds_write2_b64 v125, v[0:1], v[4:5] offset0:16 offset1:18
	v_cvt_pk_bf16_f32 v4, v12, v13
	v_cvt_pk_bf16_f32 v5, v14, v15
	v_cvt_pk_bf16_f32 v2, v16, v17
	v_cvt_pk_bf16_f32 v3, v18, v19
	v_cvt_pk_bf16_f32 v0, v20, v21
	v_cvt_pk_bf16_f32 v1, v22, v23
	ds_write2_b64 v192, v[2:3], v[0:1] offset0:80 offset1:82
	v_cvt_pk_bf16_f32 v0, v8, v9
	v_cvt_pk_bf16_f32 v1, v10, v11
	v_cvt_pk_bf16_f32 v2, v24, v25
	v_cvt_pk_bf16_f32 v3, v26, v27
	ds_write2_b64 v125, v[0:1], v[4:5] offset0:20 offset1:22
	v_cvt_pk_bf16_f32 v0, v28, v29
	v_cvt_pk_bf16_f32 v1, v30, v31
	ds_write2_b64 v192, v[2:3], v[0:1] offset0:84 offset1:86
	v_mfma_f32_32x32x16_bf16 v[0:15], v[52:55], v[36:39], 0
	v_mfma_f32_32x32x16_bf16 v[16:31], v[48:51], v[32:35], 0
	s_nop 10
	v_cvt_pk_bf16_f32 v0, v0, v1
	v_cvt_pk_bf16_f32 v1, v2, v3
	v_cvt_pk_bf16_f32 v4, v4, v5
	v_cvt_pk_bf16_f32 v5, v6, v7
	ds_write2_b64 v125, v[0:1], v[4:5] offset0:24 offset1:26
	v_cvt_pk_bf16_f32 v4, v12, v13
	v_cvt_pk_bf16_f32 v5, v14, v15
	v_cvt_pk_bf16_f32 v2, v16, v17
	v_pk_fma_f32 v[16:17], v[84:85], v[44:45], v[136:137] op_sel:[0,0,1] op_sel_hi:[0,1,0]
	v_cvt_pk_bf16_f32 v3, v18, v19
	v_pk_fma_f32 v[18:19], v[42:43], v[16:17], v[160:161]
	v_cvt_pk_bf16_f32 v0, v20, v21
	v_pk_fma_f32 v[16:17], v[84:85], v[16:17], v[18:19] op_sel:[0,0,1] op_sel_hi:[0,1,0]
	v_pk_fma_f32 v[18:19], v[86:87], v[16:17], v[162:163] op_sel:[0,1,0] op_sel_hi:[1,0,1]
	v_cvt_pk_bf16_f32 v1, v22, v23
	v_pk_fma_f32 v[16:17], v[84:85], v[16:17], v[18:19] op_sel_hi:[0,1,1]
	v_pk_fma_f32 v[18:19], v[86:87], v[16:17], v[164:165] op_sel:[0,1,0] op_sel_hi:[1,0,1]
	ds_write2_b64 v192, v[2:3], v[0:1] offset0:88 offset1:90
	v_pk_fma_f32 v[16:17], v[84:85], v[16:17], v[18:19] op_sel_hi:[0,1,1]
	v_pk_fma_f32 v[18:19], v[86:87], v[16:17], v[166:167] op_sel:[0,1,0] op_sel_hi:[1,0,1]
	v_cvt_pk_bf16_f32 v0, v8, v9
	v_pk_fma_f32 v[16:17], v[84:85], v[16:17], v[18:19] op_sel_hi:[0,1,1]
	v_pk_fma_f32 v[18:19], v[86:87], v[16:17], v[168:169] op_sel:[0,1,0] op_sel_hi:[1,0,1]
	v_cvt_pk_bf16_f32 v1, v10, v11
	v_pk_fma_f32 v[16:17], v[84:85], v[16:17], v[18:19] op_sel_hi:[0,1,1]
	v_pk_fma_f32 v[18:19], v[86:87], v[16:17], v[170:171] op_sel:[0,1,0] op_sel_hi:[1,0,1]
	v_cvt_pk_bf16_f32 v2, v24, v25
	v_pk_fma_f32 v[16:17], v[84:85], v[16:17], v[18:19] op_sel_hi:[0,1,1]
	v_cvt_pk_bf16_f32 v3, v26, v27
	ds_write2_b64 v125, v[0:1], v[4:5] offset0:28 offset1:30
	v_cvt_pk_bf16_f32 v0, v28, v29
	v_cvt_pk_bf16_f32 v1, v30, v31
	v_pk_fma_f32 v[18:19], v[86:87], v[16:17], v[172:173] op_sel:[0,1,0] op_sel_hi:[1,0,1]
	ds_write2_b64 v192, v[2:3], v[0:1] offset0:92 offset1:94
	v_pk_fma_f32 v[16:17], v[84:85], v[16:17], v[18:19] op_sel_hi:[0,1,1]
	s_waitcnt lgkmcnt(0)
	v_pk_fma_f32 v[18:19], v[86:87], v[16:17], v[174:175] op_sel:[0,1,0] op_sel_hi:[1,0,1]
	ds_read2_b32 v[0:1], v145 offset1:68
	ds_read2_b32 v[2:3], v215 offset0:128 offset1:196
	ds_read2_b32 v[6:7], v145 offset0:136 offset1:204
	ds_read2_b32 v[8:9], v216 offset0:8 offset1:76
	ds_read2_b32 v[10:11], v217 offset0:16 offset1:84
	ds_read2_b32 v[12:13], v216 offset0:144 offset1:212
	ds_read2_b32 v[14:15], v217 offset0:152 offset1:220
	ds_read2_b32 v[32:33], v210 offset0:24 offset1:92
	s_waitcnt lgkmcnt(7)
	v_lshlrev_b32_e32 v5, 16, v0
	v_and_b32_e32 v4, 0xffff0000, v0
	v_pk_fma_f32 v[16:17], v[84:85], v[16:17], v[18:19] op_sel_hi:[0,1,1]
	v_pk_fma_f32 v[4:5], v[86:87], v[16:17], v[4:5] op_sel:[0,1,0] op_sel_hi:[1,0,1]
	v_lshlrev_b32_e32 v0, 16, v1
	v_and_b32_e32 v1, 0xffff0000, v1
	v_pk_fma_f32 v[16:17], v[84:85], v[16:17], v[4:5] op_sel_hi:[0,1,1]
	v_pk_fma_f32 v[18:19], v[42:43], v[16:17], v[0:1]
	v_pk_fma_f32 v[0:1], v[80:81], v[46:47], v[138:139] op_sel:[0,0,1] op_sel_hi:[0,1,0]
	v_pk_fma_f32 v[4:5], v[40:41], v[0:1], v[140:141]
	s_waitcnt lgkmcnt(6)
	v_lshlrev_b32_e32 v21, 16, v2
	v_pk_fma_f32 v[0:1], v[80:81], v[0:1], v[4:5] op_sel:[0,0,1] op_sel_hi:[0,1,0]
	v_pk_fma_f32 v[4:5], v[82:83], v[0:1], v[142:143] op_sel:[0,1,0] op_sel_hi:[1,0,1]
	v_and_b32_e32 v20, 0xffff0000, v2
	v_pk_fma_f32 v[0:1], v[80:81], v[0:1], v[4:5] op_sel_hi:[0,1,1]
	v_pk_fma_f32 v[4:5], v[82:83], v[0:1], v[148:149] op_sel:[0,1,0] op_sel_hi:[1,0,1]
	v_lshlrev_b32_e32 v2, 16, v3
	v_pk_fma_f32 v[0:1], v[80:81], v[0:1], v[4:5] op_sel_hi:[0,1,1]
	v_pk_fma_f32 v[4:5], v[82:83], v[0:1], v[150:151] op_sel:[0,1,0] op_sel_hi:[1,0,1]
	v_and_b32_e32 v3, 0xffff0000, v3
	v_pk_fma_f32 v[0:1], v[80:81], v[0:1], v[4:5] op_sel_hi:[0,1,1]
	v_pk_fma_f32 v[4:5], v[82:83], v[0:1], v[152:153] op_sel:[0,1,0] op_sel_hi:[1,0,1]
	v_pk_fma_f32 v[16:17], v[84:85], v[16:17], v[18:19] op_sel:[0,0,1] op_sel_hi:[0,1,0]
	v_pk_fma_f32 v[0:1], v[80:81], v[0:1], v[4:5] op_sel_hi:[0,1,1]
	v_pk_fma_f32 v[4:5], v[82:83], v[0:1], v[154:155] op_sel:[0,1,0] op_sel_hi:[1,0,1]
	s_waitcnt lgkmcnt(5)
	v_lshlrev_b32_e32 v23, 16, v7
	v_pk_fma_f32 v[0:1], v[80:81], v[0:1], v[4:5] op_sel_hi:[0,1,1]
	v_pk_fma_f32 v[4:5], v[82:83], v[0:1], v[156:157] op_sel:[0,1,0] op_sel_hi:[1,0,1]
	v_and_b32_e32 v22, 0xffff0000, v7
	v_pk_fma_f32 v[0:1], v[80:81], v[0:1], v[4:5] op_sel_hi:[0,1,1]
	v_pk_fma_f32 v[4:5], v[82:83], v[0:1], v[158:159] op_sel:[0,1,0] op_sel_hi:[1,0,1]
	s_waitcnt lgkmcnt(4)
	v_lshlrev_b32_e32 v7, 16, v9
	v_pk_fma_f32 v[0:1], v[80:81], v[0:1], v[4:5] op_sel_hi:[0,1,1]
	v_pk_fma_f32 v[4:5], v[82:83], v[0:1], v[20:21] op_sel:[0,1,0] op_sel_hi:[1,0,1]
	v_lshlrev_b32_e32 v20, 16, v6
	v_pk_fma_f32 v[0:1], v[80:81], v[0:1], v[4:5] op_sel_hi:[0,1,1]
	v_and_b32_e32 v21, 0xffff0000, v6
	v_pk_fma_f32 v[2:3], v[40:41], v[0:1], v[2:3]
	v_pk_fma_f32 v[18:19], v[42:43], v[16:17], v[20:21]
	v_lshlrev_b32_e32 v4, 16, v8
	v_and_b32_e32 v5, 0xffff0000, v8
	v_pk_fma_f32 v[16:17], v[84:85], v[16:17], v[18:19] op_sel:[0,0,1] op_sel_hi:[0,1,0]
	v_pk_fma_f32 v[0:1], v[80:81], v[0:1], v[2:3] op_sel:[0,0,1] op_sel_hi:[0,1,0]
	v_pk_fma_f32 v[18:19], v[86:87], v[16:17], v[22:23] op_sel:[0,1,0] op_sel_hi:[1,0,1]
	v_pk_fma_f32 v[2:3], v[40:41], v[0:1], v[4:5]
	v_and_b32_e32 v6, 0xffff0000, v9
	s_waitcnt lgkmcnt(3)
	v_lshlrev_b32_e32 v25, 16, v10
	v_and_b32_e32 v24, 0xffff0000, v10
	v_pk_fma_f32 v[16:17], v[84:85], v[16:17], v[18:19] op_sel_hi:[0,1,1]
	v_pk_fma_f32 v[0:1], v[80:81], v[0:1], v[2:3] op_sel:[0,0,1] op_sel_hi:[0,1,0]
	v_pk_fma_f32 v[18:19], v[86:87], v[16:17], v[24:25] op_sel:[0,1,0] op_sel_hi:[1,0,1]
	v_pk_fma_f32 v[2:3], v[82:83], v[0:1], v[6:7] op_sel:[0,1,0] op_sel_hi:[1,0,1]
	s_waitcnt lgkmcnt(2)
	v_lshlrev_b32_e32 v9, 16, v12
	v_and_b32_e32 v8, 0xffff0000, v12
	v_lshlrev_b32_e32 v27, 16, v11
	v_and_b32_e32 v26, 0xffff0000, v11
	v_pk_fma_f32 v[16:17], v[84:85], v[16:17], v[18:19] op_sel_hi:[0,1,1]
	v_pk_fma_f32 v[0:1], v[80:81], v[0:1], v[2:3] op_sel_hi:[0,1,1]
	v_pk_fma_f32 v[18:19], v[86:87], v[16:17], v[26:27] op_sel:[0,1,0] op_sel_hi:[1,0,1]
	v_pk_fma_f32 v[2:3], v[82:83], v[0:1], v[8:9] op_sel:[0,1,0] op_sel_hi:[1,0,1]
	v_lshlrev_b32_e32 v11, 16, v13
	v_and_b32_e32 v10, 0xffff0000, v13
	s_waitcnt lgkmcnt(1)
	v_lshlrev_b32_e32 v29, 16, v14
	v_and_b32_e32 v28, 0xffff0000, v14
	v_pk_fma_f32 v[16:17], v[84:85], v[16:17], v[18:19] op_sel_hi:[0,1,1]
	v_pk_fma_f32 v[0:1], v[80:81], v[0:1], v[2:3] op_sel_hi:[0,1,1]
	v_pk_fma_f32 v[18:19], v[86:87], v[16:17], v[28:29] op_sel:[0,1,0] op_sel_hi:[1,0,1]
	v_pk_fma_f32 v[2:3], v[82:83], v[0:1], v[10:11] op_sel:[0,1,0] op_sel_hi:[1,0,1]
	s_waitcnt lgkmcnt(0)
	v_lshlrev_b32_e32 v13, 16, v32
	v_and_b32_e32 v12, 0xffff0000, v32
	v_lshlrev_b32_e32 v31, 16, v15
	v_and_b32_e32 v30, 0xffff0000, v15
	v_pk_fma_f32 v[16:17], v[84:85], v[16:17], v[18:19] op_sel_hi:[0,1,1]
	v_pk_fma_f32 v[0:1], v[80:81], v[0:1], v[2:3] op_sel_hi:[0,1,1]
	v_pk_fma_f32 v[18:19], v[86:87], v[16:17], v[30:31] op_sel:[0,1,0] op_sel_hi:[1,0,1]
	v_pk_fma_f32 v[2:3], v[82:83], v[0:1], v[12:13] op_sel:[0,1,0] op_sel_hi:[1,0,1]
	v_lshlrev_b32_e32 v15, 16, v33
	v_and_b32_e32 v14, 0xffff0000, v33
	ds_read2_b32 v[50:51], v211 offset0:32 offset1:100
	ds_read2_b32 v[48:49], v210 offset0:160 offset1:228
	ds_read2_b32 v[46:47], v211 offset0:168 offset1:236
	ds_read2_b32 v[44:45], v212 offset0:40 offset1:108
	ds_read2_b32 v[38:39], v213 offset0:48 offset1:116
	ds_read2_b32 v[36:37], v212 offset0:176 offset1:244
	ds_read2_b32 v[34:35], v213 offset0:184 offset1:252
	ds_read2_b32 v[32:33], v214 offset0:56 offset1:124
	s_waitcnt lgkmcnt(7)
	v_lshlrev_b32_e32 v53, 16, v50
	v_and_b32_e32 v52, 0xffff0000, v50
	v_pk_fma_f32 v[16:17], v[84:85], v[16:17], v[18:19] op_sel_hi:[0,1,1]
	v_pk_fma_f32 v[0:1], v[80:81], v[0:1], v[2:3] op_sel_hi:[0,1,1]
	v_pk_fma_f32 v[18:19], v[86:87], v[16:17], v[52:53] op_sel:[0,1,0] op_sel_hi:[1,0,1]
	v_pk_fma_f32 v[2:3], v[82:83], v[0:1], v[14:15] op_sel:[0,1,0] op_sel_hi:[1,0,1]
	s_waitcnt lgkmcnt(6)
	v_lshlrev_b32_e32 v55, 16, v48
	v_and_b32_e32 v54, 0xffff0000, v48
	v_lshlrev_b32_e32 v57, 16, v51
	v_and_b32_e32 v56, 0xffff0000, v51
	v_pk_fma_f32 v[16:17], v[84:85], v[16:17], v[18:19] op_sel_hi:[0,1,1]
	v_pk_fma_f32 v[0:1], v[80:81], v[0:1], v[2:3] op_sel_hi:[0,1,1]
	v_pk_fma_f32 v[18:19], v[86:87], v[16:17], v[56:57] op_sel:[0,1,0] op_sel_hi:[1,0,1]
	v_pk_fma_f32 v[2:3], v[82:83], v[0:1], v[54:55] op_sel:[0,1,0] op_sel_hi:[1,0,1]
	v_lshlrev_b32_e32 v51, 16, v49
	v_and_b32_e32 v50, 0xffff0000, v49
	s_waitcnt lgkmcnt(5)
	v_lshlrev_b32_e32 v49, 16, v46
	v_and_b32_e32 v48, 0xffff0000, v46
	v_pk_fma_f32 v[16:17], v[84:85], v[16:17], v[18:19] op_sel_hi:[0,1,1]
	v_pk_fma_f32 v[0:1], v[80:81], v[0:1], v[2:3] op_sel_hi:[0,1,1]
	v_pk_fma_f32 v[18:19], v[86:87], v[16:17], v[48:49] op_sel:[0,1,0] op_sel_hi:[1,0,1]
	v_pk_fma_f32 v[2:3], v[82:83], v[0:1], v[50:51] op_sel:[0,1,0] op_sel_hi:[1,0,1]
	s_waitcnt lgkmcnt(4)
	v_lshlrev_b32_e32 v59, 16, v44
	v_and_b32_e32 v58, 0xffff0000, v44
	v_lshlrev_b32_e32 v46, 16, v47
	v_and_b32_e32 v47, 0xffff0000, v47
	v_pk_fma_f32 v[16:17], v[84:85], v[16:17], v[18:19] op_sel_hi:[0,1,1]
	v_pk_fma_f32 v[0:1], v[80:81], v[0:1], v[2:3] op_sel_hi:[0,1,1]
	v_pk_fma_f32 v[18:19], v[42:43], v[16:17], v[46:47]
	v_pk_fma_f32 v[2:3], v[82:83], v[0:1], v[58:59] op_sel:[0,1,0] op_sel_hi:[1,0,1]
	v_lshlrev_b32_e32 v20, 16, v45
	v_and_b32_e32 v21, 0xffff0000, v45
	v_pk_fma_f32 v[0:1], v[80:81], v[0:1], v[2:3] op_sel_hi:[0,1,1]
	s_waitcnt lgkmcnt(3)
	v_lshlrev_b32_e32 v4, 16, v38
	v_and_b32_e32 v5, 0xffff0000, v38
	v_pk_fma_f32 v[16:17], v[84:85], v[16:17], v[18:19] op_sel:[0,0,1] op_sel_hi:[0,1,0]
	v_pk_fma_f32 v[2:3], v[40:41], v[0:1], v[20:21]
	v_pk_fma_f32 v[4:5], v[42:43], v[16:17], v[4:5]
	s_waitcnt lgkmcnt(2)
	v_lshlrev_b32_e32 v12, 16, v36
	v_and_b32_e32 v13, 0xffff0000, v36
	v_lshlrev_b32_e32 v7, 16, v39
	v_and_b32_e32 v6, 0xffff0000, v39
	v_pk_fma_f32 v[4:5], v[84:85], v[16:17], v[4:5] op_sel:[0,0,1] op_sel_hi:[0,1,0]
	v_pk_fma_f32 v[0:1], v[80:81], v[0:1], v[2:3] op_sel:[0,0,1] op_sel_hi:[0,1,0]
	v_pk_fma_f32 v[6:7], v[86:87], v[4:5], v[6:7] op_sel:[0,1,0] op_sel_hi:[1,0,1]
	v_pk_fma_f32 v[2:3], v[40:41], v[0:1], v[12:13]
	v_lshlrev_b32_e32 v15, 16, v37
	v_and_b32_e32 v14, 0xffff0000, v37
	s_waitcnt lgkmcnt(1)
	v_lshlrev_b32_e32 v21, 16, v34
	v_and_b32_e32 v20, 0xffff0000, v34
	v_pk_fma_f32 v[4:5], v[84:85], v[4:5], v[6:7] op_sel_hi:[0,1,1]
	v_pk_fma_f32 v[0:1], v[80:81], v[0:1], v[2:3] op_sel:[0,0,1] op_sel_hi:[0,1,0]
	v_pk_fma_f32 v[6:7], v[86:87], v[4:5], v[20:21] op_sel:[0,1,0] op_sel_hi:[1,0,1]
	v_pk_fma_f32 v[2:3], v[82:83], v[0:1], v[14:15] op_sel:[0,1,0] op_sel_hi:[1,0,1]
	s_waitcnt lgkmcnt(0)
	v_lshlrev_b32_e32 v23, 16, v32
	v_and_b32_e32 v22, 0xffff0000, v32
	v_lshlrev_b32_e32 v25, 16, v35
	v_and_b32_e32 v24, 0xffff0000, v35
	v_pk_fma_f32 v[4:5], v[84:85], v[4:5], v[6:7] op_sel_hi:[0,1,1]
	v_pk_fma_f32 v[0:1], v[80:81], v[0:1], v[2:3] op_sel_hi:[0,1,1]
	v_pk_fma_f32 v[6:7], v[86:87], v[4:5], v[24:25] op_sel:[0,1,0] op_sel_hi:[1,0,1]
	v_pk_fma_f32 v[2:3], v[82:83], v[0:1], v[22:23] op_sel:[0,1,0] op_sel_hi:[1,0,1]
	v_lshlrev_b32_e32 v27, 16, v33
	v_and_b32_e32 v26, 0xffff0000, v33
	ds_read2_b32 v[28:29], v202 offset0:64 offset1:132
	ds_read2_b32 v[30:31], v203 offset0:64 offset1:132
	ds_read2_b32 v[32:33], v204 offset0:72 offset1:140
	ds_read2_b32 v[34:35], v205 offset0:72 offset1:140
	ds_read2_b32 v[36:37], v206 offset0:80 offset1:148
	ds_read2_b32 v[38:39], v207 offset0:80 offset1:148
	ds_read2_b32 v[10:11], v208 offset0:88 offset1:156
	ds_read2_b32 v[8:9], v209 offset0:88 offset1:156
	s_waitcnt lgkmcnt(7)
	v_lshlrev_b32_e32 v45, 16, v28
	v_and_b32_e32 v44, 0xffff0000, v28
	v_pk_fma_f32 v[4:5], v[84:85], v[4:5], v[6:7] op_sel_hi:[0,1,1]
	v_pk_fma_f32 v[0:1], v[80:81], v[0:1], v[2:3] op_sel_hi:[0,1,1]
	v_pk_fma_f32 v[6:7], v[86:87], v[4:5], v[44:45] op_sel:[0,1,0] op_sel_hi:[1,0,1]
	v_pk_fma_f32 v[2:3], v[82:83], v[0:1], v[26:27] op_sel:[0,1,0] op_sel_hi:[1,0,1]
	s_waitcnt lgkmcnt(6)
	v_lshlrev_b32_e32 v47, 16, v30
	v_and_b32_e32 v46, 0xffff0000, v30
	v_lshlrev_b32_e32 v49, 16, v29
	v_and_b32_e32 v48, 0xffff0000, v29
	v_pk_fma_f32 v[4:5], v[84:85], v[4:5], v[6:7] op_sel_hi:[0,1,1]
	v_pk_fma_f32 v[0:1], v[80:81], v[0:1], v[2:3] op_sel_hi:[0,1,1]
	v_pk_fma_f32 v[6:7], v[86:87], v[4:5], v[48:49] op_sel:[0,1,0] op_sel_hi:[1,0,1]
	v_pk_fma_f32 v[2:3], v[82:83], v[0:1], v[46:47] op_sel:[0,1,0] op_sel_hi:[1,0,1]
	v_lshlrev_b32_e32 v29, 16, v31
	v_and_b32_e32 v28, 0xffff0000, v31
	s_waitcnt lgkmcnt(5)
	v_lshlrev_b32_e32 v31, 16, v32
	v_and_b32_e32 v30, 0xffff0000, v32
	v_pk_fma_f32 v[4:5], v[84:85], v[4:5], v[6:7] op_sel_hi:[0,1,1]
	v_pk_fma_f32 v[0:1], v[80:81], v[0:1], v[2:3] op_sel_hi:[0,1,1]
	v_pk_fma_f32 v[6:7], v[86:87], v[4:5], v[30:31] op_sel:[0,1,0] op_sel_hi:[1,0,1]
	v_pk_fma_f32 v[2:3], v[82:83], v[0:1], v[28:29] op_sel:[0,1,0] op_sel_hi:[1,0,1]
	s_waitcnt lgkmcnt(4)
	v_lshlrev_b32_e32 v51, 16, v34
	v_and_b32_e32 v50, 0xffff0000, v34
	v_lshlrev_b32_e32 v53, 16, v33
	v_and_b32_e32 v52, 0xffff0000, v33
	v_pk_fma_f32 v[4:5], v[84:85], v[4:5], v[6:7] op_sel_hi:[0,1,1]
	v_pk_fma_f32 v[0:1], v[80:81], v[0:1], v[2:3] op_sel_hi:[0,1,1]
	v_pk_fma_f32 v[6:7], v[86:87], v[4:5], v[52:53] op_sel:[0,1,0] op_sel_hi:[1,0,1]
	v_pk_fma_f32 v[2:3], v[82:83], v[0:1], v[50:51] op_sel:[0,1,0] op_sel_hi:[1,0,1]
	v_lshlrev_b32_e32 v33, 16, v35
	v_and_b32_e32 v32, 0xffff0000, v35
	s_waitcnt lgkmcnt(3)
	v_lshlrev_b32_e32 v35, 16, v36
	v_and_b32_e32 v34, 0xffff0000, v36
	v_pk_fma_f32 v[4:5], v[84:85], v[4:5], v[6:7] op_sel_hi:[0,1,1]
	v_pk_fma_f32 v[0:1], v[80:81], v[0:1], v[2:3] op_sel_hi:[0,1,1]
	v_pk_fma_f32 v[6:7], v[86:87], v[4:5], v[34:35] op_sel:[0,1,0] op_sel_hi:[1,0,1]
	v_pk_fma_f32 v[2:3], v[82:83], v[0:1], v[32:33] op_sel:[0,1,0] op_sel_hi:[1,0,1]
	s_waitcnt lgkmcnt(2)
	v_lshlrev_b32_e32 v55, 16, v38
	v_and_b32_e32 v54, 0xffff0000, v38
	v_lshlrev_b32_e32 v36, 16, v37
	v_and_b32_e32 v37, 0xffff0000, v37
	v_pk_fma_f32 v[4:5], v[84:85], v[4:5], v[6:7] op_sel_hi:[0,1,1]
	v_pk_fma_f32 v[0:1], v[80:81], v[0:1], v[2:3] op_sel_hi:[0,1,1]
	v_pk_fma_f32 v[6:7], v[42:43], v[4:5], v[36:37]
	v_pk_fma_f32 v[2:3], v[82:83], v[0:1], v[54:55] op_sel:[0,1,0] op_sel_hi:[1,0,1]
	v_lshlrev_b32_e32 v16, 16, v39
	v_and_b32_e32 v17, 0xffff0000, v39
	v_pk_fma_f32 v[0:1], v[80:81], v[0:1], v[2:3] op_sel_hi:[0,1,1]
	s_waitcnt lgkmcnt(1)
	v_lshlrev_b32_e32 v14, 16, v10
	v_and_b32_e32 v15, 0xffff0000, v10
	v_pk_fma_f32 v[4:5], v[84:85], v[4:5], v[6:7] op_sel:[0,0,1] op_sel_hi:[0,1,0]
	v_pk_fma_f32 v[2:3], v[40:41], v[0:1], v[16:17]
	v_pk_fma_f32 v[6:7], v[42:43], v[4:5], v[14:15]
	s_waitcnt lgkmcnt(0)
	v_lshlrev_b32_e32 v12, 16, v8
	v_and_b32_e32 v13, 0xffff0000, v8
	v_lshlrev_b32_e32 v17, 16, v11
	v_and_b32_e32 v16, 0xffff0000, v11
	v_pk_fma_f32 v[4:5], v[84:85], v[4:5], v[6:7] op_sel:[0,0,1] op_sel_hi:[0,1,0]
	v_pk_fma_f32 v[0:1], v[80:81], v[0:1], v[2:3] op_sel:[0,0,1] op_sel_hi:[0,1,0]
	v_pk_fma_f32 v[6:7], v[86:87], v[4:5], v[16:17] op_sel:[0,1,0] op_sel_hi:[1,0,1]
	v_pk_fma_f32 v[2:3], v[40:41], v[0:1], v[12:13]
	v_lshlrev_b32_e32 v11, 16, v9
	v_and_b32_e32 v10, 0xffff0000, v9
	ds_read2_b32 v[8:9], v194 offset0:96 offset1:164
	ds_read2_b32 v[18:19], v195 offset0:96 offset1:164
	ds_read2_b32 v[20:21], v196 offset0:104 offset1:172
	ds_read2_b32 v[22:23], v197 offset0:104 offset1:172
	ds_read2_b32 v[24:25], v198 offset0:112 offset1:180
	ds_read2_b32 v[26:27], v199 offset0:112 offset1:180
	ds_read2_b32 v[28:29], v200 offset0:120 offset1:188
	ds_read2_b32 v[30:31], v201 offset0:120 offset1:188
	s_waitcnt lgkmcnt(7)
	v_lshlrev_b32_e32 v33, 16, v8
	v_and_b32_e32 v32, 0xffff0000, v8
	v_pk_fma_f32 v[4:5], v[84:85], v[4:5], v[6:7] op_sel_hi:[0,1,1]
	v_pk_fma_f32 v[0:1], v[80:81], v[0:1], v[2:3] op_sel:[0,0,1] op_sel_hi:[0,1,0]
	v_pk_fma_f32 v[6:7], v[86:87], v[4:5], v[32:33] op_sel:[0,1,0] op_sel_hi:[1,0,1]
	v_pk_fma_f32 v[2:3], v[82:83], v[0:1], v[10:11] op_sel:[0,1,0] op_sel_hi:[1,0,1]
	s_waitcnt lgkmcnt(6)
	v_lshlrev_b32_e32 v35, 16, v18
	v_and_b32_e32 v34, 0xffff0000, v18
	v_lshlrev_b32_e32 v37, 16, v9
	v_and_b32_e32 v36, 0xffff0000, v9
	v_pk_fma_f32 v[4:5], v[84:85], v[4:5], v[6:7] op_sel_hi:[0,1,1]
	v_pk_fma_f32 v[0:1], v[80:81], v[0:1], v[2:3] op_sel_hi:[0,1,1]
	v_pk_fma_f32 v[6:7], v[86:87], v[4:5], v[36:37] op_sel:[0,1,0] op_sel_hi:[1,0,1]
	v_pk_fma_f32 v[2:3], v[82:83], v[0:1], v[34:35] op_sel:[0,1,0] op_sel_hi:[1,0,1]
	v_lshlrev_b32_e32 v9, 16, v19
	v_and_b32_e32 v8, 0xffff0000, v19
	s_waitcnt lgkmcnt(5)
	v_lshlrev_b32_e32 v19, 16, v20
	v_and_b32_e32 v18, 0xffff0000, v20
	v_pk_fma_f32 v[4:5], v[84:85], v[4:5], v[6:7] op_sel_hi:[0,1,1]
	v_pk_fma_f32 v[0:1], v[80:81], v[0:1], v[2:3] op_sel_hi:[0,1,1]
	v_pk_fma_f32 v[6:7], v[86:87], v[4:5], v[18:19] op_sel:[0,1,0] op_sel_hi:[1,0,1]
	v_pk_fma_f32 v[2:3], v[82:83], v[0:1], v[8:9] op_sel:[0,1,0] op_sel_hi:[1,0,1]
	s_waitcnt lgkmcnt(4)
	v_lshlrev_b32_e32 v39, 16, v22
	v_and_b32_e32 v38, 0xffff0000, v22
	v_lshlrev_b32_e32 v45, 16, v21
	v_and_b32_e32 v44, 0xffff0000, v21
	v_pk_fma_f32 v[4:5], v[84:85], v[4:5], v[6:7] op_sel_hi:[0,1,1]
	v_pk_fma_f32 v[0:1], v[80:81], v[0:1], v[2:3] op_sel_hi:[0,1,1]
	v_pk_fma_f32 v[6:7], v[86:87], v[4:5], v[44:45] op_sel:[0,1,0] op_sel_hi:[1,0,1]
	v_pk_fma_f32 v[2:3], v[82:83], v[0:1], v[38:39] op_sel:[0,1,0] op_sel_hi:[1,0,1]
	v_lshlrev_b32_e32 v21, 16, v23
	v_and_b32_e32 v20, 0xffff0000, v23
	s_waitcnt lgkmcnt(3)
	v_lshlrev_b32_e32 v23, 16, v24
	v_and_b32_e32 v22, 0xffff0000, v24
	v_pk_fma_f32 v[4:5], v[84:85], v[4:5], v[6:7] op_sel_hi:[0,1,1]
	v_pk_fma_f32 v[0:1], v[80:81], v[0:1], v[2:3] op_sel_hi:[0,1,1]
	v_pk_fma_f32 v[6:7], v[86:87], v[4:5], v[22:23] op_sel:[0,1,0] op_sel_hi:[1,0,1]
	v_pk_fma_f32 v[2:3], v[82:83], v[0:1], v[20:21] op_sel:[0,1,0] op_sel_hi:[1,0,1]
	s_waitcnt lgkmcnt(2)
	v_lshlrev_b32_e32 v47, 16, v26
	v_and_b32_e32 v46, 0xffff0000, v26
	v_lshlrev_b32_e32 v49, 16, v25
	v_and_b32_e32 v48, 0xffff0000, v25
	v_pk_fma_f32 v[4:5], v[84:85], v[4:5], v[6:7] op_sel_hi:[0,1,1]
	v_pk_fma_f32 v[0:1], v[80:81], v[0:1], v[2:3] op_sel_hi:[0,1,1]
	v_pk_fma_f32 v[6:7], v[86:87], v[4:5], v[48:49] op_sel:[0,1,0] op_sel_hi:[1,0,1]
	v_pk_fma_f32 v[2:3], v[82:83], v[0:1], v[46:47] op_sel:[0,1,0] op_sel_hi:[1,0,1]
	v_lshlrev_b32_e32 v25, 16, v27
	v_and_b32_e32 v24, 0xffff0000, v27
	s_waitcnt lgkmcnt(1)
	v_lshlrev_b32_e32 v27, 16, v28
	v_and_b32_e32 v26, 0xffff0000, v28
	v_pk_fma_f32 v[4:5], v[84:85], v[4:5], v[6:7] op_sel_hi:[0,1,1]
	v_pk_fma_f32 v[0:1], v[80:81], v[0:1], v[2:3] op_sel_hi:[0,1,1]
	v_pk_fma_f32 v[6:7], v[86:87], v[4:5], v[26:27] op_sel:[0,1,0] op_sel_hi:[1,0,1]
	v_pk_fma_f32 v[2:3], v[82:83], v[0:1], v[24:25] op_sel:[0,1,0] op_sel_hi:[1,0,1]
	s_waitcnt lgkmcnt(0)
	v_lshlrev_b32_e32 v51, 16, v30
	v_and_b32_e32 v50, 0xffff0000, v30
	v_lshlrev_b32_e32 v53, 16, v29
	v_and_b32_e32 v52, 0xffff0000, v29
	v_pk_fma_f32 v[4:5], v[84:85], v[4:5], v[6:7] op_sel_hi:[0,1,1]
	v_pk_fma_f32 v[0:1], v[80:81], v[0:1], v[2:3] op_sel_hi:[0,1,1]
	v_pk_fma_f32 v[6:7], v[86:87], v[4:5], v[52:53] op_sel:[0,1,0] op_sel_hi:[1,0,1]
	v_pk_fma_f32 v[2:3], v[82:83], v[0:1], v[50:51] op_sel:[0,1,0] op_sel_hi:[1,0,1]
	v_pk_fma_f32 v[4:5], v[84:85], v[4:5], v[6:7] op_sel_hi:[0,1,1]
	v_lshlrev_b32_e32 v7, 16, v31
	v_and_b32_e32 v6, 0xffff0000, v31
	v_pk_fma_f32 v[0:1], v[80:81], v[0:1], v[2:3] op_sel_hi:[0,1,1]
	v_pk_fma_f32 v[2:3], v[82:83], v[0:1], v[6:7] op_sel:[0,1,0] op_sel_hi:[1,0,1]
	s_waitcnt lgkmcnt(0)
	s_nop 0
	v_pk_fma_f32 v[0:1], v[80:81], v[0:1], v[2:3] op_sel_hi:[0,1,1]
	v_pk_mov_b32 v[2:3], v[4:5], v[4:5] op_sel:[1,0]
	v_lshl_add_u64 v[4:5], v[90:91], 0, s[20:21]
	global_store_dwordx2 v[4:5], v[2:3], off
	v_pk_mov_b32 v[0:1], v[0:1], v[0:1] op_sel:[1,0]
	v_lshl_add_u64 v[2:3], v[90:91], 0, s[10:11]
	global_store_dwordx2 v[2:3], v[0:1], off
	s_cbranch_scc0 .LBB0_326
